# loop-edge edit (guide 7.11): K-loop counter/pointer/exit-test SALU moved in front of the loop-back barrier in all six 8-phase GEMM loops (v80 base)
# baseline (speedup 1.0000x reference)
; #define PG8_STAGE(bufoff, gbase, voff) do { _Pragma("unroll") for (int _i = 0; _i < 2; ++_i) \
;         __builtin_amdgcn_global_load_lds((const unsigned*)((const char*)(gbase) + (voff)[_i]), (LAS unsigned*)(lds + (bufoff) + ldsw + _i * 8192), 16, 0, 0); } while (0)
; #define PG8_LDA(dst, b, h) do { _Pragma("unroll") for (int m = 0; m < 4; ++m) _Pragma("unroll") for (int k = 0; k < 2; ++k) dst[m][k] = *(const LAS bf16x8*)(lds + PG8_SA(b, h) + aoff + m * 2048 + k * 1024); } while (0)
; #define PG8_LDB(dst, b, h) do { _Pragma("unroll") for (int n = 0; n < 2; ++n) _Pragma("unroll") for (int k = 0; k < 2; ++k) dst[n][k] = *(const LAS bf16x8*)(lds + PG8_SB(b, h) + boff + n * 2048 + k * 1024); } while (0)
; #define PG8_MMA(ai, bj, At, Bt) do { __builtin_amdgcn_s_setprio(1); _Pragma("unroll") for (int m = 0; m < 4; ++m) _Pragma("unroll") for (int n = 0; n < 2; ++n) _Pragma("unroll") for (int k = 0; k < 2; ++k) \
;         acc[ai][bj][m][n] = __builtin_amdgcn_mfma_f32_16x16x32_bf16(Bt[n][k], At[m][k], acc[ai][bj][m][n], 0, 0, 0); __builtin_amdgcn_s_setprio(0); } while (0)
; #define PG8_BAR __builtin_amdgcn_s_barrier()
; template <class Epi, class Sched>
; __device__ __forceinline__ void gemm_phase(LAS unsigned char* lds, const Gemm g, const Sched& S, const Epi& E) {
;     ...
;         for (int t = 0; t < nt; t += 2) {
;             const bool last = (t == nt - 2);
;             const char* a1 = cA + (size_t)(t + 1) * kstep;
;             const char* a2 = last ? nA : cA + (size_t)(t + 2) * kstep; const char* b2 = last ? nB : cB + (size_t)(t + 2) * kstep;
;             const char* a3 = a2 + kstep; const char* b3 = b2 + kstep;
;             PG8_LDB(B0, 0, 0); PG8_LDB(B1, 0, 1); PG8_SCHED; PG8_LDA(At, 0, 0); PG8_STAGE(PG8_SA(1, 1), a1 + hstepA, voffA);
;             PG8_WAIT_V(8); PG8_WAIT_L(0); PG8_BAR; PG8_MMA(0, 0, At, B0); PG8_MMA(0, 1, At, B1); PG8_BAR; PG8_SCHED;
;             PG8_LDA(At, 0, 1); PG8_STAGE(PG8_SB(0, 0), b2, voffB); PG8_STAGE(PG8_SB(0, 1), b2 + hstepB, voffB); PG8_STAGE(PG8_SA(0, 0), a2, voffA);
;             PG8_WAIT_V(8); PG8_WAIT_L(0); PG8_BAR; PG8_MMA(1, 0, At, B0); PG8_MMA(1, 1, At, B1); PG8_BAR; PG8_SCHED;
;             PG8_LDB(B0, 1, 0); PG8_LDB(B1, 1, 1); PG8_SCHED; PG8_LDA(At, 1, 0); PG8_STAGE(PG8_SA(0, 1), a2 + hstepA, voffA);
;             PG8_WAIT_V(8); PG8_WAIT_L(0); PG8_BAR; PG8_MMA(0, 0, At, B0); PG8_MMA(0, 1, At, B1); PG8_BAR; PG8_SCHED;
.LBB0_176:
	ds_read_b128 v[144:147], v152
	ds_read_b128 v[156:159], v152 offset:1024
	ds_read_b128 v[160:163], v152 offset:2048
	ds_read_b128 v[164:167], v152 offset:3072
	ds_read_b128 v[168:171], v153
	ds_read_b128 v[172:175], v153 offset:1024
	ds_read_b128 v[176:179], v153 offset:2048
	ds_read_b128 v[180:183], v153 offset:3072
	s_add_u32 s28, s26, 0x100
	s_addc_u32 s29, s27, 0
	s_cmp_eq_u32 s53, 28
	s_cselect_b32 s35, s19, s29
	s_cselect_b32 s34, s49, s28
	s_cselect_b32 s31, s17, s52
	s_cselect_b32 s30, s50, s51
	v_lshl_add_u64 v[222:223], s[26:27], 0, v[136:137]
	s_add_i32 m0, s25, 0xc000
	ds_read_b128 v[190:193], v154
	ds_read_b128 v[194:197], v154 offset:1024
	ds_read_b128 v[198:201], v154 offset:2048
	ds_read_b128 v[202:205], v154 offset:3072
	ds_read_b128 v[206:209], v154 offset:4096
	ds_read_b128 v[210:213], v154 offset:5120
	ds_read_b128 v[214:217], v154 offset:6144
	ds_read_b128 v[218:221], v154 offset:7168
	global_load_lds_dwordx4 v[222:223], off
	v_lshl_add_u64 v[222:223], s[26:27], 0, v[138:139]
	s_add_i32 m0, s25, 0xe000
	s_nop 0
	global_load_lds_dwordx4 v[222:223], off
	s_waitcnt vmcnt(8)
	s_waitcnt lgkmcnt(0)
	s_barrier
	s_setprio 1
	s_waitcnt lgkmcnt(0)
	v_mfma_f32_16x16x32_bf16 v[124:127], v[144:147], v[190:193], v[124:127]
	v_mfma_f32_16x16x32_bf16 v[120:123], v[160:163], v[190:193], v[120:123]
	v_mfma_f32_16x16x32_bf16 v[116:119], v[144:147], v[198:201], v[116:119]
	v_mfma_f32_16x16x32_bf16 v[108:111], v[160:163], v[198:201], v[108:111]
	v_mfma_f32_16x16x32_bf16 v[100:103], v[144:147], v[206:209], v[100:103]
	v_mfma_f32_16x16x32_bf16 v[92:95], v[160:163], v[206:209], v[92:95]
	v_mfma_f32_16x16x32_bf16 v[84:87], v[144:147], v[214:217], v[84:87]
	v_mfma_f32_16x16x32_bf16 v[76:79], v[160:163], v[214:217], v[76:79]
	v_mfma_f32_16x16x32_bf16 v[124:127], v[156:159], v[194:197], v[124:127]
	v_mfma_f32_16x16x32_bf16 v[120:123], v[164:167], v[194:197], v[120:123]
	v_mfma_f32_16x16x32_bf16 v[116:119], v[156:159], v[202:205], v[116:119]
	v_mfma_f32_16x16x32_bf16 v[108:111], v[164:167], v[202:205], v[108:111]
	v_mfma_f32_16x16x32_bf16 v[100:103], v[156:159], v[210:213], v[100:103]
	v_mfma_f32_16x16x32_bf16 v[92:95], v[164:167], v[210:213], v[92:95]
	v_mfma_f32_16x16x32_bf16 v[84:87], v[156:159], v[218:221], v[84:87]
	v_mfma_f32_16x16x32_bf16 v[76:79], v[164:167], v[218:221], v[76:79]
	s_setprio 0
	s_setprio 1
	v_mfma_f32_16x16x32_bf16 v[112:115], v[168:171], v[190:193], v[112:115]
	v_mfma_f32_16x16x32_bf16 v[104:107], v[176:179], v[190:193], v[104:107]
	v_mfma_f32_16x16x32_bf16 v[96:99], v[168:171], v[198:201], v[96:99]
	v_mfma_f32_16x16x32_bf16 v[88:91], v[176:179], v[198:201], v[88:91]
	v_mfma_f32_16x16x32_bf16 v[80:83], v[168:171], v[206:209], v[80:83]
	v_mfma_f32_16x16x32_bf16 v[72:75], v[176:179], v[206:209], v[72:75]
	v_mfma_f32_16x16x32_bf16 v[68:71], v[168:171], v[214:217], v[68:71]
	v_mfma_f32_16x16x32_bf16 v[64:67], v[176:179], v[214:217], v[64:67]
	v_mfma_f32_16x16x32_bf16 v[112:115], v[172:175], v[194:197], v[112:115]
	v_mfma_f32_16x16x32_bf16 v[104:107], v[180:183], v[194:197], v[104:107]
	v_mfma_f32_16x16x32_bf16 v[96:99], v[172:175], v[202:205], v[96:99]
	v_mfma_f32_16x16x32_bf16 v[88:91], v[180:183], v[202:205], v[88:91]
	v_mfma_f32_16x16x32_bf16 v[80:83], v[172:175], v[210:213], v[80:83]
	v_mfma_f32_16x16x32_bf16 v[72:75], v[180:183], v[210:213], v[72:75]
	v_mfma_f32_16x16x32_bf16 v[68:71], v[172:175], v[218:221], v[68:71]
	v_mfma_f32_16x16x32_bf16 v[64:67], v[180:183], v[218:221], v[64:67]
	s_setprio 0
	s_barrier
	s_add_i32 s26, s45, s36
	v_lshl_add_u64 v[222:223], s[30:31], 0, v[130:131]
	s_mov_b32 m0, s26
	ds_read_b128 v[190:193], v154 offset:16384
	ds_read_b128 v[194:197], v154 offset:17408
	ds_read_b128 v[198:201], v154 offset:18432
	ds_read_b128 v[202:205], v154 offset:19456
	ds_read_b128 v[206:209], v154 offset:20480
	ds_read_b128 v[210:213], v154 offset:21504
	ds_read_b128 v[214:217], v154 offset:22528
	ds_read_b128 v[218:221], v154 offset:23552
	global_load_lds_dwordx4 v[222:223], off
	s_add_i32 m0, s26, 0x2000
	s_add_u32 s26, s30, 0x80000
	v_lshl_add_u64 v[224:225], s[30:31], 0, v[134:135]
	s_addc_u32 s27, s31, 0
	s_add_i32 s54, s46, s36
	global_load_lds_dwordx4 v[224:225], off
	v_lshl_add_u64 v[226:227], s[26:27], 0, v[130:131]
	s_mov_b32 m0, s54
	v_lshl_add_u64 v[228:229], s[34:35], 0, v[132:133]
	global_load_lds_dwordx4 v[226:227], off
	v_lshl_add_u64 v[226:227], s[26:27], 0, v[134:135]
	s_add_i32 m0, s54, 0x2000
	s_nop 0
	global_load_lds_dwordx4 v[226:227], off
	v_lshl_add_u64 v[226:227], s[34:35], 0, v[128:129]
	s_mov_b32 m0, s25
	s_nop 0
	global_load_lds_dwordx4 v[226:227], off
	s_mov_b32 m0, s37
	s_nop 0
	global_load_lds_dwordx4 v[228:229], off
	s_waitcnt vmcnt(8)
	s_waitcnt lgkmcnt(0)
	s_barrier
; #define PG8_STAGE(bufoff, gbase, voff) do { _Pragma("unroll") for (int _i = 0; _i < 2; ++_i) \
;         __builtin_amdgcn_global_load_lds((const unsigned*)((const char*)(gbase) + (voff)[_i]), (LAS unsigned*)(lds + (bufoff) + ldsw + _i * 8192), 16, 0, 0); } while (0)
; #define PG8_LDA(dst, b, h) do { _Pragma("unroll") for (int m = 0; m < 4; ++m) _Pragma("unroll") for (int k = 0; k < 2; ++k) dst[m][k] = *(const LAS bf16x8*)(lds + PG8_SA(b, h) + aoff + m * 2048 + k * 1024); } while (0)
; #define PG8_LDB(dst, b, h) do { _Pragma("unroll") for (int n = 0; n < 2; ++n) _Pragma("unroll") for (int k = 0; k < 2; ++k) dst[n][k] = *(const LAS bf16x8*)(lds + PG8_SB(b, h) + boff + n * 2048 + k * 1024); } while (0)
; #define PG8_MMA(ai, bj, At, Bt) do { __builtin_amdgcn_s_setprio(1); _Pragma("unroll") for (int m = 0; m < 4; ++m) _Pragma("unroll") for (int n = 0; n < 2; ++n) _Pragma("unroll") for (int k = 0; k < 2; ++k) \
;         acc[ai][bj][m][n] = __builtin_amdgcn_mfma_f32_16x16x32_bf16(Bt[n][k], At[m][k], acc[ai][bj][m][n], 0, 0, 0); __builtin_amdgcn_s_setprio(0); } while (0)
; #define PG8_WAIT_V(n) asm volatile("s_waitcnt vmcnt(" #n ")" ::: "memory")
; #define PG8_WAIT_L(n) asm volatile("s_waitcnt lgkmcnt(" #n ")" ::: "memory")
; #define PG8_BAR __builtin_amdgcn_s_barrier()
; #define PG8_SCHED __builtin_amdgcn_sched_barrier(0)
; template <class Epi, class Sched>
; __device__ __forceinline__ void gemm_phase(LAS unsigned char* lds, const Gemm g, const Sched& S, const Epi& E) {
;     ...
;             PG8_WAIT_V(8); PG8_WAIT_L(0); PG8_BAR; PG8_MMA(1, 0, At, B0); PG8_MMA(1, 1, At, B1); PG8_BAR; PG8_SCHED;
;             PG8_LDB(B0, 1, 0); PG8_LDB(B1, 1, 1); PG8_SCHED; PG8_LDA(At, 1, 0); PG8_STAGE(PG8_SA(0, 1), a2 + hstepA, voffA);
;             PG8_WAIT_V(8); PG8_WAIT_L(0); PG8_BAR; PG8_MMA(0, 0, At, B0); PG8_MMA(0, 1, At, B1); PG8_BAR; PG8_SCHED;
	s_setprio 1
	s_waitcnt lgkmcnt(0)
	v_mfma_f32_16x16x32_bf16 v[60:63], v[144:147], v[190:193], v[60:63]
	v_mfma_f32_16x16x32_bf16 v[56:59], v[160:163], v[190:193], v[56:59]
	v_mfma_f32_16x16x32_bf16 v[52:55], v[144:147], v[198:201], v[52:55]
	v_mfma_f32_16x16x32_bf16 v[44:47], v[160:163], v[198:201], v[44:47]
	v_mfma_f32_16x16x32_bf16 v[36:39], v[144:147], v[206:209], v[36:39]
	v_mfma_f32_16x16x32_bf16 v[28:31], v[160:163], v[206:209], v[28:31]
	v_mfma_f32_16x16x32_bf16 v[20:23], v[144:147], v[214:217], v[20:23]
	v_mfma_f32_16x16x32_bf16 v[12:15], v[160:163], v[214:217], v[12:15]
	v_mfma_f32_16x16x32_bf16 v[60:63], v[156:159], v[194:197], v[60:63]
	v_mfma_f32_16x16x32_bf16 v[56:59], v[164:167], v[194:197], v[56:59]
	v_mfma_f32_16x16x32_bf16 v[52:55], v[156:159], v[202:205], v[52:55]
	v_mfma_f32_16x16x32_bf16 v[44:47], v[164:167], v[202:205], v[44:47]
	v_mfma_f32_16x16x32_bf16 v[36:39], v[156:159], v[210:213], v[36:39]
	v_mfma_f32_16x16x32_bf16 v[28:31], v[164:167], v[210:213], v[28:31]
	v_mfma_f32_16x16x32_bf16 v[20:23], v[156:159], v[218:221], v[20:23]
	v_mfma_f32_16x16x32_bf16 v[12:15], v[164:167], v[218:221], v[12:15]
	s_setprio 0
	s_setprio 1
	v_mfma_f32_16x16x32_bf16 v[48:51], v[168:171], v[190:193], v[48:51]
	v_mfma_f32_16x16x32_bf16 v[40:43], v[176:179], v[190:193], v[40:43]
	v_mfma_f32_16x16x32_bf16 v[32:35], v[168:171], v[198:201], v[32:35]
	v_mfma_f32_16x16x32_bf16 v[24:27], v[176:179], v[198:201], v[24:27]
	v_mfma_f32_16x16x32_bf16 v[16:19], v[168:171], v[206:209], v[16:19]
	v_mfma_f32_16x16x32_bf16 v[8:11], v[176:179], v[206:209], v[8:11]
	v_mfma_f32_16x16x32_bf16 v[4:7], v[168:171], v[214:217], v[4:7]
	v_mfma_f32_16x16x32_bf16 v[0:3], v[176:179], v[214:217], v[0:3]
	v_mfma_f32_16x16x32_bf16 v[48:51], v[172:175], v[194:197], v[48:51]
	v_mfma_f32_16x16x32_bf16 v[40:43], v[180:183], v[194:197], v[40:43]
	v_mfma_f32_16x16x32_bf16 v[32:35], v[172:175], v[202:205], v[32:35]
	v_mfma_f32_16x16x32_bf16 v[24:27], v[180:183], v[202:205], v[24:27]
	v_mfma_f32_16x16x32_bf16 v[16:19], v[172:175], v[210:213], v[16:19]
	v_mfma_f32_16x16x32_bf16 v[8:11], v[180:183], v[210:213], v[8:11]
	v_mfma_f32_16x16x32_bf16 v[4:7], v[172:175], v[218:221], v[4:7]
	v_mfma_f32_16x16x32_bf16 v[0:3], v[180:183], v[218:221], v[0:3]
	s_setprio 0
	s_barrier
	s_add_i32 s54, 0, 0x18000
	v_add_u32_e32 v155, s54, v150
	s_add_i32 s55, 0, 0x1c000
	ds_read_b128 v[144:147], v155
	ds_read_b128 v[156:159], v155 offset:1024
	ds_read_b128 v[160:163], v155 offset:2048
	ds_read_b128 v[164:167], v155 offset:3072
	v_add_u32_e32 v155, s55, v150
	ds_read_b128 v[168:171], v155
	ds_read_b128 v[172:175], v155 offset:1024
	ds_read_b128 v[176:179], v155 offset:2048
	ds_read_b128 v[180:183], v155 offset:3072
	s_add_u32 s26, s34, 0x80000
	s_addc_u32 s27, s35, 0
	s_mov_b32 m0, s38
	v_lshl_add_u64 v[230:231], s[26:27], 0, v[128:129]
	ds_read_b128 v[190:193], v154 offset:32768
	ds_read_b128 v[194:197], v154 offset:33792
	ds_read_b128 v[198:201], v154 offset:34816
	ds_read_b128 v[202:205], v154 offset:35840
	ds_read_b128 v[206:209], v154 offset:36864
	ds_read_b128 v[210:213], v154 offset:37888
	ds_read_b128 v[214:217], v154 offset:38912
	ds_read_b128 v[218:221], v154 offset:39936
	global_load_lds_dwordx4 v[230:231], off
	v_lshl_add_u64 v[230:231], s[26:27], 0, v[132:133]
	s_mov_b32 m0, s39
	s_nop 0
	global_load_lds_dwordx4 v[230:231], off
	s_waitcnt vmcnt(8)
	s_waitcnt lgkmcnt(0)
	s_barrier
	s_setprio 1
	s_waitcnt lgkmcnt(0)
	v_mfma_f32_16x16x32_bf16 v[124:127], v[144:147], v[190:193], v[124:127]
	v_mfma_f32_16x16x32_bf16 v[120:123], v[160:163], v[190:193], v[120:123]
	v_mfma_f32_16x16x32_bf16 v[116:119], v[144:147], v[198:201], v[116:119]
	v_mfma_f32_16x16x32_bf16 v[108:111], v[160:163], v[198:201], v[108:111]
	v_mfma_f32_16x16x32_bf16 v[100:103], v[144:147], v[206:209], v[100:103]
	v_mfma_f32_16x16x32_bf16 v[92:95], v[160:163], v[206:209], v[92:95]
	v_mfma_f32_16x16x32_bf16 v[84:87], v[144:147], v[214:217], v[84:87]
	v_mfma_f32_16x16x32_bf16 v[76:79], v[160:163], v[214:217], v[76:79]
	v_mfma_f32_16x16x32_bf16 v[124:127], v[156:159], v[194:197], v[124:127]
	v_mfma_f32_16x16x32_bf16 v[120:123], v[164:167], v[194:197], v[120:123]
	v_mfma_f32_16x16x32_bf16 v[116:119], v[156:159], v[202:205], v[116:119]
	v_mfma_f32_16x16x32_bf16 v[108:111], v[164:167], v[202:205], v[108:111]
	v_mfma_f32_16x16x32_bf16 v[100:103], v[156:159], v[210:213], v[100:103]
	v_mfma_f32_16x16x32_bf16 v[92:95], v[164:167], v[210:213], v[92:95]
	v_mfma_f32_16x16x32_bf16 v[84:87], v[156:159], v[218:221], v[84:87]
	v_mfma_f32_16x16x32_bf16 v[76:79], v[164:167], v[218:221], v[76:79]
	s_setprio 0
	s_setprio 1
	v_mfma_f32_16x16x32_bf16 v[112:115], v[168:171], v[190:193], v[112:115]
	v_mfma_f32_16x16x32_bf16 v[104:107], v[176:179], v[190:193], v[104:107]
	v_mfma_f32_16x16x32_bf16 v[96:99], v[168:171], v[198:201], v[96:99]
	v_mfma_f32_16x16x32_bf16 v[88:91], v[176:179], v[198:201], v[88:91]
	v_mfma_f32_16x16x32_bf16 v[80:83], v[168:171], v[206:209], v[80:83]
	v_mfma_f32_16x16x32_bf16 v[72:75], v[176:179], v[206:209], v[72:75]
	v_mfma_f32_16x16x32_bf16 v[68:71], v[168:171], v[214:217], v[68:71]
	v_mfma_f32_16x16x32_bf16 v[64:67], v[176:179], v[214:217], v[64:67]
	v_mfma_f32_16x16x32_bf16 v[112:115], v[172:175], v[194:197], v[112:115]
	v_mfma_f32_16x16x32_bf16 v[104:107], v[180:183], v[194:197], v[104:107]
	v_mfma_f32_16x16x32_bf16 v[96:99], v[172:175], v[202:205], v[96:99]
	v_mfma_f32_16x16x32_bf16 v[88:91], v[180:183], v[202:205], v[88:91]
	v_mfma_f32_16x16x32_bf16 v[80:83], v[172:175], v[210:213], v[80:83]
	v_mfma_f32_16x16x32_bf16 v[72:75], v[180:183], v[210:213], v[72:75]
	v_mfma_f32_16x16x32_bf16 v[68:71], v[172:175], v[218:221], v[68:71]
	v_mfma_f32_16x16x32_bf16 v[64:67], v[180:183], v[218:221], v[64:67]
	s_setprio 0
	s_barrier
; #define PG8_STAGE(bufoff, gbase, voff) do { _Pragma("unroll") for (int _i = 0; _i < 2; ++_i) \
;         __builtin_amdgcn_global_load_lds((const unsigned*)((const char*)(gbase) + (voff)[_i]), (LAS unsigned*)(lds + (bufoff) + ldsw + _i * 8192), 16, 0, 0); } while (0)
; #define PG8_LDA(dst, b, h) do { _Pragma("unroll") for (int m = 0; m < 4; ++m) _Pragma("unroll") for (int k = 0; k < 2; ++k) dst[m][k] = *(const LAS bf16x8*)(lds + PG8_SA(b, h) + aoff + m * 2048 + k * 1024); } while (0)
; #define PG8_MMA(ai, bj, At, Bt) do { __builtin_amdgcn_s_setprio(1); _Pragma("unroll") for (int m = 0; m < 4; ++m) _Pragma("unroll") for (int n = 0; n < 2; ++n) _Pragma("unroll") for (int k = 0; k < 2; ++k) \
;         acc[ai][bj][m][n] = __builtin_amdgcn_mfma_f32_16x16x32_bf16(Bt[n][k], At[m][k], acc[ai][bj][m][n], 0, 0, 0); __builtin_amdgcn_s_setprio(0); } while (0)
; #define PG8_WAIT_V(n) asm volatile("s_waitcnt vmcnt(" #n ")" ::: "memory")
; #define PG8_WAIT_L(n) asm volatile("s_waitcnt lgkmcnt(" #n ")" ::: "memory")
; #define PG8_BAR __builtin_amdgcn_s_barrier()
; #define PG8_SCHED __builtin_amdgcn_sched_barrier(0)
; template <class Epi, class Sched>
; __device__ __forceinline__ void gemm_phase(LAS unsigned char* lds, const Gemm g, const Sched& S, const Epi& E) {
;     ...
;             PG8_LDA(At, 1, 1); PG8_STAGE(PG8_SB(1, 0), b3, voffB); PG8_STAGE(PG8_SB(1, 1), b3 + hstepB, voffB); PG8_STAGE(PG8_SA(1, 0), a3, voffA);
;             PG8_WAIT_V(8); PG8_WAIT_L(0); PG8_BAR; PG8_MMA(1, 0, At, B0); PG8_MMA(1, 1, At, B1); PG8_BAR; PG8_SCHED;
;         }
	s_add_i32 s26, s54, s36
	v_lshl_add_u64 v[222:223], v[222:223], 0, s[12:13]
	s_mov_b32 m0, s26
	ds_read_b128 v[190:193], v154 offset:49152
	ds_read_b128 v[194:197], v154 offset:50176
	ds_read_b128 v[198:201], v154 offset:51200
	ds_read_b128 v[202:205], v154 offset:52224
	ds_read_b128 v[206:209], v154 offset:53248
	ds_read_b128 v[210:213], v154 offset:54272
	ds_read_b128 v[214:217], v154 offset:55296
	ds_read_b128 v[218:221], v154 offset:56320
	global_load_lds_dwordx4 v[222:223], off
	s_add_i32 m0, s26, 0x2000
	s_add_u32 s26, s30, 0x80080
	v_lshl_add_u64 v[222:223], v[224:225], 0, s[12:13]
	s_addc_u32 s27, s31, 0
	s_add_i32 s30, s55, s36
	global_load_lds_dwordx4 v[222:223], off
	v_lshl_add_u64 v[222:223], s[26:27], 0, v[130:131]
	s_mov_b32 m0, s30
	s_nop 0
	global_load_lds_dwordx4 v[222:223], off
	v_lshl_add_u64 v[222:223], s[26:27], 0, v[134:135]
	s_add_i32 m0, s30, 0x2000
	s_nop 0
	global_load_lds_dwordx4 v[222:223], off
	v_lshl_add_u64 v[222:223], v[226:227], 0, s[12:13]
	s_mov_b32 m0, s41
	s_nop 0
	global_load_lds_dwordx4 v[222:223], off
	v_lshl_add_u64 v[222:223], v[228:229], 0, s[12:13]
	s_mov_b32 m0, s42
	s_nop 0
	global_load_lds_dwordx4 v[222:223], off
	s_waitcnt vmcnt(8)
	s_waitcnt lgkmcnt(0)
	s_barrier
	s_setprio 1
	s_waitcnt lgkmcnt(0)
	v_mfma_f32_16x16x32_bf16 v[60:63], v[144:147], v[190:193], v[60:63]
	v_mfma_f32_16x16x32_bf16 v[56:59], v[160:163], v[190:193], v[56:59]
	v_mfma_f32_16x16x32_bf16 v[52:55], v[144:147], v[198:201], v[52:55]
	v_mfma_f32_16x16x32_bf16 v[44:47], v[160:163], v[198:201], v[44:47]
	v_mfma_f32_16x16x32_bf16 v[36:39], v[144:147], v[206:209], v[36:39]
	v_mfma_f32_16x16x32_bf16 v[28:31], v[160:163], v[206:209], v[28:31]
	v_mfma_f32_16x16x32_bf16 v[20:23], v[144:147], v[214:217], v[20:23]
	v_mfma_f32_16x16x32_bf16 v[12:15], v[160:163], v[214:217], v[12:15]
	v_mfma_f32_16x16x32_bf16 v[60:63], v[156:159], v[194:197], v[60:63]
	v_mfma_f32_16x16x32_bf16 v[56:59], v[164:167], v[194:197], v[56:59]
	v_mfma_f32_16x16x32_bf16 v[52:55], v[156:159], v[202:205], v[52:55]
	v_mfma_f32_16x16x32_bf16 v[44:47], v[164:167], v[202:205], v[44:47]
	v_mfma_f32_16x16x32_bf16 v[36:39], v[156:159], v[210:213], v[36:39]
	v_mfma_f32_16x16x32_bf16 v[28:31], v[164:167], v[210:213], v[28:31]
	v_mfma_f32_16x16x32_bf16 v[20:23], v[156:159], v[218:221], v[20:23]
	v_mfma_f32_16x16x32_bf16 v[12:15], v[164:167], v[218:221], v[12:15]
	s_setprio 0
	s_setprio 1
	v_mfma_f32_16x16x32_bf16 v[48:51], v[168:171], v[190:193], v[48:51]
	v_mfma_f32_16x16x32_bf16 v[40:43], v[176:179], v[190:193], v[40:43]
	v_mfma_f32_16x16x32_bf16 v[32:35], v[168:171], v[198:201], v[32:35]
	v_mfma_f32_16x16x32_bf16 v[24:27], v[176:179], v[198:201], v[24:27]
	v_mfma_f32_16x16x32_bf16 v[16:19], v[168:171], v[206:209], v[16:19]
	v_mfma_f32_16x16x32_bf16 v[8:11], v[176:179], v[206:209], v[8:11]
	v_mfma_f32_16x16x32_bf16 v[4:7], v[168:171], v[214:217], v[4:7]
	v_mfma_f32_16x16x32_bf16 v[0:3], v[176:179], v[214:217], v[0:3]
	v_mfma_f32_16x16x32_bf16 v[48:51], v[172:175], v[194:197], v[48:51]
	v_mfma_f32_16x16x32_bf16 v[40:43], v[180:183], v[194:197], v[40:43]
	v_mfma_f32_16x16x32_bf16 v[32:35], v[172:175], v[202:205], v[32:35]
	v_mfma_f32_16x16x32_bf16 v[24:27], v[180:183], v[202:205], v[24:27]
	v_mfma_f32_16x16x32_bf16 v[16:19], v[172:175], v[210:213], v[16:19]
	v_mfma_f32_16x16x32_bf16 v[8:11], v[180:183], v[210:213], v[8:11]
	v_mfma_f32_16x16x32_bf16 v[4:7], v[172:175], v[218:221], v[4:7]
	v_mfma_f32_16x16x32_bf16 v[0:3], v[180:183], v[218:221], v[0:3]
	s_setprio 0
	s_add_i32 s53, s53, 2
	s_add_u32 s51, s51, 0x100
	s_addc_u32 s52, s52, 0
	s_cmp_gt_u32 s53, 29
	s_mov_b64 s[26:27], s[28:29]
	s_barrier
	s_cbranch_scc0 .LBB0_176
	s_and_b64 vcc, exec, s[14:15]
	s_cbranch_vccz .LBB0_179
	s_barrier

; #define PG8_STAGE(bufoff, gbase, voff) do { _Pragma("unroll") for (int _i = 0; _i < 2; ++_i) \
;         __builtin_amdgcn_global_load_lds((const unsigned*)((const char*)(gbase) + (voff)[_i]), (LAS unsigned*)(lds + (bufoff) + ldsw + _i * 8192), 16, 0, 0); } while (0)
; #define PG8_LDA(dst, b, h) do { _Pragma("unroll") for (int m = 0; m < 4; ++m) _Pragma("unroll") for (int k = 0; k < 2; ++k) dst[m][k] = *(const LAS bf16x8*)(lds + PG8_SA(b, h) + aoff + m * 2048 + k * 1024); } while (0)
; #define PG8_LDB(dst, b, h) do { _Pragma("unroll") for (int n = 0; n < 2; ++n) _Pragma("unroll") for (int k = 0; k < 2; ++k) dst[n][k] = *(const LAS bf16x8*)(lds + PG8_SB(b, h) + boff + n * 2048 + k * 1024); } while (0)
; #define PG8_MMA(ai, bj, At, Bt) do { __builtin_amdgcn_s_setprio(1); _Pragma("unroll") for (int m = 0; m < 4; ++m) _Pragma("unroll") for (int n = 0; n < 2; ++n) _Pragma("unroll") for (int k = 0; k < 2; ++k) \
;         acc[ai][bj][m][n] = __builtin_amdgcn_mfma_f32_16x16x32_bf16(Bt[n][k], At[m][k], acc[ai][bj][m][n], 0, 0, 0); __builtin_amdgcn_s_setprio(0); } while (0)
; #define PG8_WAIT_V(n) asm volatile("s_waitcnt vmcnt(" #n ")" ::: "memory")
; #define PG8_WAIT_L(n) asm volatile("s_waitcnt lgkmcnt(" #n ")" ::: "memory")
; #define PG8_BAR __builtin_amdgcn_s_barrier()
; #define PG8_SCHED __builtin_amdgcn_sched_barrier(0)
; template <class Epi, class Sched>
; __device__ __forceinline__ void gemm_phase(LAS unsigned char* lds, const Gemm g, const Sched& S, const Epi& E) {
;     ...
;         for (int t = 0; t < nt; t += 2) {
;             const bool last = (t == nt - 2);
;             const char* a1 = cA + (size_t)(t + 1) * kstep;
;             const char* a2 = last ? nA : cA + (size_t)(t + 2) * kstep; const char* b2 = last ? nB : cB + (size_t)(t + 2) * kstep;
;             const char* a3 = a2 + kstep; const char* b3 = b2 + kstep;
;             PG8_LDB(B0, 0, 0); PG8_LDB(B1, 0, 1); PG8_SCHED; PG8_LDA(At, 0, 0); PG8_STAGE(PG8_SA(1, 1), a1 + hstepA, voffA);
;             PG8_WAIT_V(8); PG8_WAIT_L(0); PG8_BAR; PG8_MMA(0, 0, At, B0); PG8_MMA(0, 1, At, B1); PG8_BAR; PG8_SCHED;
;             PG8_LDA(At, 0, 1); PG8_STAGE(PG8_SB(0, 0), b2, voffB); PG8_STAGE(PG8_SB(0, 1), b2 + hstepB, voffB); PG8_STAGE(PG8_SA(0, 0), a2, voffA);
.LBB0_669:
	ds_read_b128 v[104:107], v200
	ds_read_b128 v[116:119], v200 offset:1024
	ds_read_b128 v[128:131], v200 offset:2048
	ds_read_b128 v[140:143], v200 offset:3072
	ds_read_b128 v[144:147], v201
	ds_read_b128 v[148:151], v201 offset:1024
	ds_read_b128 v[152:155], v201 offset:2048
	ds_read_b128 v[164:167], v201 offset:3072
	s_add_u32 s6, s0, 0xfff40080
	s_addc_u32 s7, s1, -1
	s_cmp_eq_u32 s46, 12
	s_cselect_b32 s9, s23, s7
	s_cselect_b32 s8, s22, s6
	s_cselect_b32 s7, s25, s45
	s_cselect_b32 s6, s24, s44
	v_lshl_add_u64 v[220:221], s[0:1], 0, v[156:157]
	s_add_i32 m0, s27, 0xc000
	ds_read_b128 v[168:171], v202
	ds_read_b128 v[172:175], v202 offset:1024
	ds_read_b128 v[204:207], v202 offset:2048
	ds_read_b128 v[208:211], v202 offset:3072
	ds_read_b128 v[212:215], v202 offset:4096
	ds_read_b128 v[216:219], v202 offset:5120
	ds_read_b128 v[224:227], v202 offset:6144
	ds_read_b128 v[228:231], v202 offset:7168
	global_load_lds_dwordx4 v[220:221], off
	v_lshl_add_u64 v[220:221], s[0:1], 0, v[158:159]
	s_add_i32 m0, s27, 0xe000
	s_nop 0
	global_load_lds_dwordx4 v[220:221], off
	s_waitcnt vmcnt(8)
	s_waitcnt lgkmcnt(0)
	s_barrier
	s_setprio 1
	s_waitcnt lgkmcnt(0)
	v_mfma_f32_16x16x32_bf16 v[136:139], v[104:107], v[168:171], v[136:139]
	v_mfma_f32_16x16x32_bf16 v[132:135], v[128:131], v[168:171], v[132:135]
	v_mfma_f32_16x16x32_bf16 v[112:115], v[104:107], v[204:207], v[112:115]
	v_mfma_f32_16x16x32_bf16 v[108:111], v[128:131], v[204:207], v[108:111]
	v_mfma_f32_16x16x32_bf16 v[92:95], v[104:107], v[212:215], v[92:95]
	v_mfma_f32_16x16x32_bf16 v[88:91], v[128:131], v[212:215], v[88:91]
	v_mfma_f32_16x16x32_bf16 v[76:79], v[104:107], v[224:227], v[76:79]
	v_mfma_f32_16x16x32_bf16 v[72:75], v[128:131], v[224:227], v[72:75]
	v_mfma_f32_16x16x32_bf16 v[136:139], v[116:119], v[172:175], v[136:139]
	v_mfma_f32_16x16x32_bf16 v[132:135], v[140:143], v[172:175], v[132:135]
	v_mfma_f32_16x16x32_bf16 v[112:115], v[116:119], v[208:211], v[112:115]
	v_mfma_f32_16x16x32_bf16 v[108:111], v[140:143], v[208:211], v[108:111]
	v_mfma_f32_16x16x32_bf16 v[92:95], v[116:119], v[216:219], v[92:95]
	v_mfma_f32_16x16x32_bf16 v[88:91], v[140:143], v[216:219], v[88:91]
	v_mfma_f32_16x16x32_bf16 v[76:79], v[116:119], v[228:231], v[76:79]
	v_mfma_f32_16x16x32_bf16 v[72:75], v[140:143], v[228:231], v[72:75]
	s_setprio 0
	s_setprio 1
	v_mfma_f32_16x16x32_bf16 v[124:127], v[144:147], v[168:171], v[124:127]
	v_mfma_f32_16x16x32_bf16 v[120:123], v[152:155], v[168:171], v[120:123]
	v_mfma_f32_16x16x32_bf16 v[100:103], v[144:147], v[204:207], v[100:103]
	v_mfma_f32_16x16x32_bf16 v[96:99], v[152:155], v[204:207], v[96:99]
	v_mfma_f32_16x16x32_bf16 v[84:87], v[144:147], v[212:215], v[84:87]
	v_mfma_f32_16x16x32_bf16 v[80:83], v[152:155], v[212:215], v[80:83]
	v_mfma_f32_16x16x32_bf16 v[68:71], v[144:147], v[224:227], v[68:71]
	v_mfma_f32_16x16x32_bf16 v[64:67], v[152:155], v[224:227], v[64:67]
	v_mfma_f32_16x16x32_bf16 v[124:127], v[148:151], v[172:175], v[124:127]
	v_mfma_f32_16x16x32_bf16 v[120:123], v[164:167], v[172:175], v[120:123]
	v_mfma_f32_16x16x32_bf16 v[100:103], v[148:151], v[208:211], v[100:103]
	v_mfma_f32_16x16x32_bf16 v[96:99], v[164:167], v[208:211], v[96:99]
	v_mfma_f32_16x16x32_bf16 v[84:87], v[148:151], v[216:219], v[84:87]
	v_mfma_f32_16x16x32_bf16 v[80:83], v[164:167], v[216:219], v[80:83]
	v_mfma_f32_16x16x32_bf16 v[68:71], v[148:151], v[228:231], v[68:71]
	v_mfma_f32_16x16x32_bf16 v[64:67], v[164:167], v[228:231], v[64:67]
	s_setprio 0
	s_barrier
	s_add_i32 s47, s37, s26
	v_lshl_add_u64 v[220:221], s[6:7], 0, v[192:193]
	s_mov_b32 m0, s47
	ds_read_b128 v[168:171], v202 offset:16384
	ds_read_b128 v[172:175], v202 offset:17408
	ds_read_b128 v[204:207], v202 offset:18432
	ds_read_b128 v[208:211], v202 offset:19456
	ds_read_b128 v[212:215], v202 offset:20480
	ds_read_b128 v[216:219], v202 offset:21504
	ds_read_b128 v[224:227], v202 offset:22528
	ds_read_b128 v[228:231], v202 offset:23552
	global_load_lds_dwordx4 v[220:221], off
	s_add_i32 m0, s47, 0x2000
	s_add_u32 s48, s6, 0xc0000
	v_lshl_add_u64 v[232:233], s[6:7], 0, v[196:197]
	s_addc_u32 s49, s7, 0
	s_add_i32 s47, s38, s26
	global_load_lds_dwordx4 v[232:233], off
	v_lshl_add_u64 v[234:235], s[48:49], 0, v[192:193]
	s_mov_b32 m0, s47
	v_lshl_add_u64 v[236:237], s[8:9], 0, v[194:195]
	global_load_lds_dwordx4 v[234:235], off
	v_lshl_add_u64 v[234:235], s[48:49], 0, v[196:197]
	s_add_i32 m0, s47, 0x2000
	s_nop 0
	global_load_lds_dwordx4 v[234:235], off
	v_lshl_add_u64 v[234:235], s[8:9], 0, v[190:191]
	s_mov_b32 m0, s27
	s_nop 0
	global_load_lds_dwordx4 v[234:235], off
	s_mov_b32 m0, s28
	s_nop 0
	global_load_lds_dwordx4 v[236:237], off
	s_waitcnt vmcnt(8)
	s_waitcnt lgkmcnt(0)
	s_barrier
; #define PG8_STAGE(bufoff, gbase, voff) do { _Pragma("unroll") for (int _i = 0; _i < 2; ++_i) \
;         __builtin_amdgcn_global_load_lds((const unsigned*)((const char*)(gbase) + (voff)[_i]), (LAS unsigned*)(lds + (bufoff) + ldsw + _i * 8192), 16, 0, 0); } while (0)
; #define PG8_LDA(dst, b, h) do { _Pragma("unroll") for (int m = 0; m < 4; ++m) _Pragma("unroll") for (int k = 0; k < 2; ++k) dst[m][k] = *(const LAS bf16x8*)(lds + PG8_SA(b, h) + aoff + m * 2048 + k * 1024); } while (0)
; #define PG8_LDB(dst, b, h) do { _Pragma("unroll") for (int n = 0; n < 2; ++n) _Pragma("unroll") for (int k = 0; k < 2; ++k) dst[n][k] = *(const LAS bf16x8*)(lds + PG8_SB(b, h) + boff + n * 2048 + k * 1024); } while (0)
; #define PG8_MMA(ai, bj, At, Bt) do { __builtin_amdgcn_s_setprio(1); _Pragma("unroll") for (int m = 0; m < 4; ++m) _Pragma("unroll") for (int n = 0; n < 2; ++n) _Pragma("unroll") for (int k = 0; k < 2; ++k) \
;         acc[ai][bj][m][n] = __builtin_amdgcn_mfma_f32_16x16x32_bf16(Bt[n][k], At[m][k], acc[ai][bj][m][n], 0, 0, 0); __builtin_amdgcn_s_setprio(0); } while (0)
; #define PG8_WAIT_V(n) asm volatile("s_waitcnt vmcnt(" #n ")" ::: "memory")
; #define PG8_WAIT_L(n) asm volatile("s_waitcnt lgkmcnt(" #n ")" ::: "memory")
; #define PG8_BAR __builtin_amdgcn_s_barrier()
; #define PG8_SCHED __builtin_amdgcn_sched_barrier(0)
; template <class Epi, class Sched>
; __device__ __forceinline__ void gemm_phase(LAS unsigned char* lds, const Gemm g, const Sched& S, const Epi& E) {
;     ...
;             PG8_WAIT_V(8); PG8_WAIT_L(0); PG8_BAR; PG8_MMA(1, 0, At, B0); PG8_MMA(1, 1, At, B1); PG8_BAR; PG8_SCHED;
;             PG8_LDB(B0, 1, 0); PG8_LDB(B1, 1, 1); PG8_SCHED; PG8_LDA(At, 1, 0); PG8_STAGE(PG8_SA(0, 1), a2 + hstepA, voffA);
;             PG8_WAIT_V(8); PG8_WAIT_L(0); PG8_BAR; PG8_MMA(0, 0, At, B0); PG8_MMA(0, 1, At, B1); PG8_BAR; PG8_SCHED;
	s_setprio 1
	s_waitcnt lgkmcnt(0)
	v_mfma_f32_16x16x32_bf16 v[60:63], v[104:107], v[168:171], v[60:63]
	v_mfma_f32_16x16x32_bf16 v[56:59], v[128:131], v[168:171], v[56:59]
	v_mfma_f32_16x16x32_bf16 v[44:47], v[104:107], v[204:207], v[44:47]
	v_mfma_f32_16x16x32_bf16 v[40:43], v[128:131], v[204:207], v[40:43]
	v_mfma_f32_16x16x32_bf16 v[28:31], v[104:107], v[212:215], v[28:31]
	v_mfma_f32_16x16x32_bf16 v[24:27], v[128:131], v[212:215], v[24:27]
	v_mfma_f32_16x16x32_bf16 v[12:15], v[104:107], v[224:227], v[12:15]
	v_mfma_f32_16x16x32_bf16 v[8:11], v[128:131], v[224:227], v[8:11]
	v_mfma_f32_16x16x32_bf16 v[60:63], v[116:119], v[172:175], v[60:63]
	v_mfma_f32_16x16x32_bf16 v[56:59], v[140:143], v[172:175], v[56:59]
	v_mfma_f32_16x16x32_bf16 v[44:47], v[116:119], v[208:211], v[44:47]
	v_mfma_f32_16x16x32_bf16 v[40:43], v[140:143], v[208:211], v[40:43]
	v_mfma_f32_16x16x32_bf16 v[28:31], v[116:119], v[216:219], v[28:31]
	v_mfma_f32_16x16x32_bf16 v[24:27], v[140:143], v[216:219], v[24:27]
	v_mfma_f32_16x16x32_bf16 v[12:15], v[116:119], v[228:231], v[12:15]
	v_mfma_f32_16x16x32_bf16 v[8:11], v[140:143], v[228:231], v[8:11]
	s_setprio 0
	s_setprio 1
	v_mfma_f32_16x16x32_bf16 v[52:55], v[144:147], v[168:171], v[52:55]
	v_mfma_f32_16x16x32_bf16 v[48:51], v[152:155], v[168:171], v[48:51]
	v_mfma_f32_16x16x32_bf16 v[36:39], v[144:147], v[204:207], v[36:39]
	v_mfma_f32_16x16x32_bf16 v[32:35], v[152:155], v[204:207], v[32:35]
	v_mfma_f32_16x16x32_bf16 v[20:23], v[144:147], v[212:215], v[20:23]
	v_mfma_f32_16x16x32_bf16 v[16:19], v[152:155], v[212:215], v[16:19]
	v_mfma_f32_16x16x32_bf16 v[4:7], v[144:147], v[224:227], v[4:7]
	v_mfma_f32_16x16x32_bf16 v[0:3], v[152:155], v[224:227], v[0:3]
	v_mfma_f32_16x16x32_bf16 v[52:55], v[148:151], v[172:175], v[52:55]
	v_mfma_f32_16x16x32_bf16 v[48:51], v[164:167], v[172:175], v[48:51]
	v_mfma_f32_16x16x32_bf16 v[36:39], v[148:151], v[208:211], v[36:39]
	v_mfma_f32_16x16x32_bf16 v[32:35], v[164:167], v[208:211], v[32:35]
	v_mfma_f32_16x16x32_bf16 v[20:23], v[148:151], v[216:219], v[20:23]
	v_mfma_f32_16x16x32_bf16 v[16:19], v[164:167], v[216:219], v[16:19]
	v_mfma_f32_16x16x32_bf16 v[4:7], v[148:151], v[228:231], v[4:7]
	v_mfma_f32_16x16x32_bf16 v[0:3], v[164:167], v[228:231], v[0:3]
	s_setprio 0
	s_barrier
	s_add_i32 s47, 0, 0x18000
	s_add_i32 s48, 0, 0x1c000
	v_add_u32_e32 v140, s47, v198
	v_add_u32_e32 v164, s48, v198
	ds_read_b128 v[104:107], v140
	ds_read_b128 v[116:119], v140 offset:1024
	ds_read_b128 v[128:131], v140 offset:2048
	ds_read_b128 v[140:143], v140 offset:3072
	ds_read_b128 v[144:147], v164
	ds_read_b128 v[148:151], v164 offset:1024
	ds_read_b128 v[152:155], v164 offset:2048
	ds_read_b128 v[164:167], v164 offset:3072
	s_add_u32 s8, s8, 0xc0000
	s_addc_u32 s9, s9, 0
	s_mov_b32 m0, s29
	v_lshl_add_u64 v[238:239], s[8:9], 0, v[190:191]
	ds_read_b128 v[168:171], v202 offset:32768
	ds_read_b128 v[172:175], v202 offset:33792
	ds_read_b128 v[204:207], v202 offset:34816
	ds_read_b128 v[208:211], v202 offset:35840
	ds_read_b128 v[212:215], v202 offset:36864
	ds_read_b128 v[216:219], v202 offset:37888
	ds_read_b128 v[224:227], v202 offset:38912
	ds_read_b128 v[228:231], v202 offset:39936
	global_load_lds_dwordx4 v[238:239], off
	v_lshl_add_u64 v[238:239], s[8:9], 0, v[194:195]
	s_mov_b32 m0, s30
	s_nop 0
	global_load_lds_dwordx4 v[238:239], off
	s_waitcnt vmcnt(8)
	s_waitcnt lgkmcnt(0)
	s_barrier
	s_setprio 1
	s_waitcnt lgkmcnt(0)
	v_mfma_f32_16x16x32_bf16 v[136:139], v[104:107], v[168:171], v[136:139]
	v_mfma_f32_16x16x32_bf16 v[132:135], v[128:131], v[168:171], v[132:135]
	v_mfma_f32_16x16x32_bf16 v[112:115], v[104:107], v[204:207], v[112:115]
	v_mfma_f32_16x16x32_bf16 v[108:111], v[128:131], v[204:207], v[108:111]
	v_mfma_f32_16x16x32_bf16 v[92:95], v[104:107], v[212:215], v[92:95]
	v_mfma_f32_16x16x32_bf16 v[88:91], v[128:131], v[212:215], v[88:91]
	v_mfma_f32_16x16x32_bf16 v[76:79], v[104:107], v[224:227], v[76:79]
	v_mfma_f32_16x16x32_bf16 v[72:75], v[128:131], v[224:227], v[72:75]
	v_mfma_f32_16x16x32_bf16 v[136:139], v[116:119], v[172:175], v[136:139]
	v_mfma_f32_16x16x32_bf16 v[132:135], v[140:143], v[172:175], v[132:135]
	v_mfma_f32_16x16x32_bf16 v[112:115], v[116:119], v[208:211], v[112:115]
	v_mfma_f32_16x16x32_bf16 v[108:111], v[140:143], v[208:211], v[108:111]
	v_mfma_f32_16x16x32_bf16 v[92:95], v[116:119], v[216:219], v[92:95]
	v_mfma_f32_16x16x32_bf16 v[88:91], v[140:143], v[216:219], v[88:91]
	v_mfma_f32_16x16x32_bf16 v[76:79], v[116:119], v[228:231], v[76:79]
	v_mfma_f32_16x16x32_bf16 v[72:75], v[140:143], v[228:231], v[72:75]
	s_setprio 0
	s_setprio 1
	v_mfma_f32_16x16x32_bf16 v[124:127], v[144:147], v[168:171], v[124:127]
	v_mfma_f32_16x16x32_bf16 v[120:123], v[152:155], v[168:171], v[120:123]
	v_mfma_f32_16x16x32_bf16 v[100:103], v[144:147], v[204:207], v[100:103]
	v_mfma_f32_16x16x32_bf16 v[96:99], v[152:155], v[204:207], v[96:99]
	v_mfma_f32_16x16x32_bf16 v[84:87], v[144:147], v[212:215], v[84:87]
	v_mfma_f32_16x16x32_bf16 v[80:83], v[152:155], v[212:215], v[80:83]
	v_mfma_f32_16x16x32_bf16 v[68:71], v[144:147], v[224:227], v[68:71]
	v_mfma_f32_16x16x32_bf16 v[64:67], v[152:155], v[224:227], v[64:67]
	v_mfma_f32_16x16x32_bf16 v[124:127], v[148:151], v[172:175], v[124:127]
	v_mfma_f32_16x16x32_bf16 v[120:123], v[164:167], v[172:175], v[120:123]
	v_mfma_f32_16x16x32_bf16 v[100:103], v[148:151], v[208:211], v[100:103]
	v_mfma_f32_16x16x32_bf16 v[96:99], v[164:167], v[208:211], v[96:99]
	v_mfma_f32_16x16x32_bf16 v[84:87], v[148:151], v[216:219], v[84:87]
	v_mfma_f32_16x16x32_bf16 v[80:83], v[164:167], v[216:219], v[80:83]
	v_mfma_f32_16x16x32_bf16 v[68:71], v[148:151], v[228:231], v[68:71]
	v_mfma_f32_16x16x32_bf16 v[64:67], v[164:167], v[228:231], v[64:67]
	s_setprio 0
	s_barrier
; #define PG8_STAGE(bufoff, gbase, voff) do { _Pragma("unroll") for (int _i = 0; _i < 2; ++_i) \
;         __builtin_amdgcn_global_load_lds((const unsigned*)((const char*)(gbase) + (voff)[_i]), (LAS unsigned*)(lds + (bufoff) + ldsw + _i * 8192), 16, 0, 0); } while (0)
; #define PG8_LDA(dst, b, h) do { _Pragma("unroll") for (int m = 0; m < 4; ++m) _Pragma("unroll") for (int k = 0; k < 2; ++k) dst[m][k] = *(const LAS bf16x8*)(lds + PG8_SA(b, h) + aoff + m * 2048 + k * 1024); } while (0)
; #define PG8_MMA(ai, bj, At, Bt) do { __builtin_amdgcn_s_setprio(1); _Pragma("unroll") for (int m = 0; m < 4; ++m) _Pragma("unroll") for (int n = 0; n < 2; ++n) _Pragma("unroll") for (int k = 0; k < 2; ++k) \
;         acc[ai][bj][m][n] = __builtin_amdgcn_mfma_f32_16x16x32_bf16(Bt[n][k], At[m][k], acc[ai][bj][m][n], 0, 0, 0); __builtin_amdgcn_s_setprio(0); } while (0)
; #define PG8_WAIT_V(n) asm volatile("s_waitcnt vmcnt(" #n ")" ::: "memory")
; #define PG8_WAIT_L(n) asm volatile("s_waitcnt lgkmcnt(" #n ")" ::: "memory")
; #define PG8_BAR __builtin_amdgcn_s_barrier()
; #define PG8_SCHED __builtin_amdgcn_sched_barrier(0)
; template <class Epi, class Sched>
; __device__ __forceinline__ void gemm_phase(LAS unsigned char* lds, const Gemm g, const Sched& S, const Epi& E) {
;     ...
;             PG8_LDA(At, 1, 1); PG8_STAGE(PG8_SB(1, 0), b3, voffB); PG8_STAGE(PG8_SB(1, 1), b3 + hstepB, voffB); PG8_STAGE(PG8_SA(1, 0), a3, voffA);
;             PG8_WAIT_V(8); PG8_WAIT_L(0); PG8_BAR; PG8_MMA(1, 0, At, B0); PG8_MMA(1, 1, At, B1); PG8_BAR; PG8_SCHED;
;         }
	s_add_i32 s8, s47, s26
	v_lshl_add_u64 v[220:221], v[220:221], 0, s[18:19]
	s_mov_b32 m0, s8
	ds_read_b128 v[168:171], v202 offset:49152
	ds_read_b128 v[172:175], v202 offset:50176
	ds_read_b128 v[204:207], v202 offset:51200
	ds_read_b128 v[208:211], v202 offset:52224
	ds_read_b128 v[212:215], v202 offset:53248
	ds_read_b128 v[216:219], v202 offset:54272
	ds_read_b128 v[224:227], v202 offset:55296
	ds_read_b128 v[228:231], v202 offset:56320
	global_load_lds_dwordx4 v[220:221], off
	s_add_i32 m0, s8, 0x2000
	s_add_u32 s6, s6, 0xc0080
	v_lshl_add_u64 v[220:221], v[232:233], 0, s[18:19]
	s_addc_u32 s7, s7, 0
	s_add_i32 s8, s48, s26
	global_load_lds_dwordx4 v[220:221], off
	v_lshl_add_u64 v[220:221], s[6:7], 0, v[192:193]
	s_mov_b32 m0, s8
	s_nop 0
	global_load_lds_dwordx4 v[220:221], off
	v_lshl_add_u64 v[220:221], s[6:7], 0, v[196:197]
	s_add_i32 m0, s8, 0x2000
	s_nop 0
	global_load_lds_dwordx4 v[220:221], off
	v_lshl_add_u64 v[220:221], v[234:235], 0, s[18:19]
	s_mov_b32 m0, s33
	s_nop 0
	global_load_lds_dwordx4 v[220:221], off
	v_lshl_add_u64 v[220:221], v[236:237], 0, s[18:19]
	s_mov_b32 m0, s34
	s_nop 0
	global_load_lds_dwordx4 v[220:221], off
	s_waitcnt vmcnt(8)
	s_waitcnt lgkmcnt(0)
	s_barrier
	s_setprio 1
	s_waitcnt lgkmcnt(0)
	v_mfma_f32_16x16x32_bf16 v[60:63], v[104:107], v[168:171], v[60:63]
	v_mfma_f32_16x16x32_bf16 v[56:59], v[128:131], v[168:171], v[56:59]
	v_mfma_f32_16x16x32_bf16 v[44:47], v[104:107], v[204:207], v[44:47]
	v_mfma_f32_16x16x32_bf16 v[40:43], v[128:131], v[204:207], v[40:43]
	v_mfma_f32_16x16x32_bf16 v[28:31], v[104:107], v[212:215], v[28:31]
	v_mfma_f32_16x16x32_bf16 v[24:27], v[128:131], v[212:215], v[24:27]
	v_mfma_f32_16x16x32_bf16 v[12:15], v[104:107], v[224:227], v[12:15]
	v_mfma_f32_16x16x32_bf16 v[8:11], v[128:131], v[224:227], v[8:11]
	v_mfma_f32_16x16x32_bf16 v[60:63], v[116:119], v[172:175], v[60:63]
	v_mfma_f32_16x16x32_bf16 v[56:59], v[140:143], v[172:175], v[56:59]
	v_mfma_f32_16x16x32_bf16 v[44:47], v[116:119], v[208:211], v[44:47]
	v_mfma_f32_16x16x32_bf16 v[40:43], v[140:143], v[208:211], v[40:43]
	v_mfma_f32_16x16x32_bf16 v[28:31], v[116:119], v[216:219], v[28:31]
	v_mfma_f32_16x16x32_bf16 v[24:27], v[140:143], v[216:219], v[24:27]
	v_mfma_f32_16x16x32_bf16 v[12:15], v[116:119], v[228:231], v[12:15]
	v_mfma_f32_16x16x32_bf16 v[8:11], v[140:143], v[228:231], v[8:11]
	s_setprio 0
	s_setprio 1
	v_mfma_f32_16x16x32_bf16 v[52:55], v[144:147], v[168:171], v[52:55]
	v_mfma_f32_16x16x32_bf16 v[48:51], v[152:155], v[168:171], v[48:51]
	v_mfma_f32_16x16x32_bf16 v[36:39], v[144:147], v[204:207], v[36:39]
	v_mfma_f32_16x16x32_bf16 v[32:35], v[152:155], v[204:207], v[32:35]
	v_mfma_f32_16x16x32_bf16 v[20:23], v[144:147], v[212:215], v[20:23]
	v_mfma_f32_16x16x32_bf16 v[16:19], v[152:155], v[212:215], v[16:19]
	v_mfma_f32_16x16x32_bf16 v[4:7], v[144:147], v[224:227], v[4:7]
	v_mfma_f32_16x16x32_bf16 v[0:3], v[152:155], v[224:227], v[0:3]
	v_mfma_f32_16x16x32_bf16 v[52:55], v[148:151], v[172:175], v[52:55]
	v_mfma_f32_16x16x32_bf16 v[48:51], v[164:167], v[172:175], v[48:51]
	v_mfma_f32_16x16x32_bf16 v[36:39], v[148:151], v[208:211], v[36:39]
	v_mfma_f32_16x16x32_bf16 v[32:35], v[164:167], v[208:211], v[32:35]
	v_mfma_f32_16x16x32_bf16 v[20:23], v[148:151], v[216:219], v[20:23]
	v_mfma_f32_16x16x32_bf16 v[16:19], v[164:167], v[216:219], v[16:19]
	v_mfma_f32_16x16x32_bf16 v[4:7], v[148:151], v[228:231], v[4:7]
	v_mfma_f32_16x16x32_bf16 v[0:3], v[164:167], v[228:231], v[0:3]
	s_setprio 0
	s_add_i32 s46, s46, 2
	s_add_u32 s0, s0, 0x100
	s_addc_u32 s1, s1, 0
	s_add_u32 s44, s44, 0x100
	s_addc_u32 s45, s45, 0
	s_cmp_gt_u32 s46, 13
	s_barrier
	s_cbranch_scc0 .LBB0_669
	s_and_b64 vcc, exec, s[20:21]
	s_cbranch_vccz .LBB0_672
	s_barrier

; #define PG8_STAGE(bufoff, gbase, voff) do { _Pragma("unroll") for (int _i = 0; _i < 2; ++_i) \
;         __builtin_amdgcn_global_load_lds((const unsigned*)((const char*)(gbase) + (voff)[_i]), (LAS unsigned*)(lds + (bufoff) + ldsw + _i * 8192), 16, 0, 0); } while (0)
; #define PG8_LDA(dst, b, h) do { _Pragma("unroll") for (int m = 0; m < 4; ++m) _Pragma("unroll") for (int k = 0; k < 2; ++k) dst[m][k] = *(const LAS bf16x8*)(lds + PG8_SA(b, h) + aoff + m * 2048 + k * 1024); } while (0)
; #define PG8_LDB(dst, b, h) do { _Pragma("unroll") for (int n = 0; n < 2; ++n) _Pragma("unroll") for (int k = 0; k < 2; ++k) dst[n][k] = *(const LAS bf16x8*)(lds + PG8_SB(b, h) + boff + n * 2048 + k * 1024); } while (0)
; #define PG8_MMA(ai, bj, At, Bt) do { __builtin_amdgcn_s_setprio(1); _Pragma("unroll") for (int m = 0; m < 4; ++m) _Pragma("unroll") for (int n = 0; n < 2; ++n) _Pragma("unroll") for (int k = 0; k < 2; ++k) \
;         acc[ai][bj][m][n] = __builtin_amdgcn_mfma_f32_16x16x32_bf16(Bt[n][k], At[m][k], acc[ai][bj][m][n], 0, 0, 0); __builtin_amdgcn_s_setprio(0); } while (0)
; #define PG8_WAIT_V(n) asm volatile("s_waitcnt vmcnt(" #n ")" ::: "memory")
; #define PG8_WAIT_L(n) asm volatile("s_waitcnt lgkmcnt(" #n ")" ::: "memory")
; #define PG8_BAR __builtin_amdgcn_s_barrier()
; #define PG8_SCHED __builtin_amdgcn_sched_barrier(0)
; template <class Epi, class Sched>
; __device__ __forceinline__ void gemm_phase(LAS unsigned char* lds, const Gemm g, const Sched& S, const Epi& E) {
;     ...
;         for (int t = 0; t < nt; t += 2) {
;             const bool last = (t == nt - 2);
;             const char* a1 = cA + (size_t)(t + 1) * kstep;
;             const char* a2 = last ? nA : cA + (size_t)(t + 2) * kstep; const char* b2 = last ? nB : cB + (size_t)(t + 2) * kstep;
;             const char* a3 = a2 + kstep; const char* b3 = b2 + kstep;
;             PG8_LDB(B0, 0, 0); PG8_LDB(B1, 0, 1); PG8_SCHED; PG8_LDA(At, 0, 0); PG8_STAGE(PG8_SA(1, 1), a1 + hstepA, voffA);
;             PG8_WAIT_V(8); PG8_WAIT_L(0); PG8_BAR; PG8_MMA(0, 0, At, B0); PG8_MMA(0, 1, At, B1); PG8_BAR; PG8_SCHED;
;             PG8_LDA(At, 0, 1); PG8_STAGE(PG8_SB(0, 0), b2, voffB); PG8_STAGE(PG8_SB(0, 1), b2 + hstepB, voffB); PG8_STAGE(PG8_SA(0, 0), a2, voffA);
.LBB0_697:
	ds_read_b128 v[88:91], v226
	ds_read_b128 v[92:95], v226 offset:1024
	ds_read_b128 v[104:107], v226 offset:2048
	ds_read_b128 v[108:111], v226 offset:3072
	ds_read_b128 v[120:123], v227
	ds_read_b128 v[124:127], v227 offset:1024
	ds_read_b128 v[136:139], v227 offset:2048
	ds_read_b128 v[140:143], v227 offset:3072
	s_add_u32 s20, s18, 0xfff40080
	s_addc_u32 s21, s19, -1
	s_cmp_eq_u32 s48, 28
	s_cselect_b32 s23, s7, s21
	s_cselect_b32 s22, s6, s20
	s_cselect_b32 s21, s17, s47
	s_cselect_b32 s20, s16, s46
	v_lshl_add_u64 v[214:215], s[18:19], 0, v[198:199]
	s_add_i32 m0, s29, 0xc000
	ds_read_b128 v[152:155], v228
	ds_read_b128 v[156:159], v228 offset:1024
	ds_read_b128 v[168:171], v228 offset:2048
	ds_read_b128 v[172:175], v228 offset:3072
	ds_read_b128 v[176:179], v228 offset:4096
	ds_read_b128 v[180:183], v228 offset:5120
	ds_read_b128 v[206:209], v228 offset:6144
	ds_read_b128 v[210:213], v228 offset:7168
	global_load_lds_dwordx4 v[214:215], off
	v_lshl_add_u64 v[214:215], s[18:19], 0, v[200:201]
	s_add_i32 m0, s29, 0xe000
	s_nop 0
	global_load_lds_dwordx4 v[214:215], off
	s_waitcnt vmcnt(8)
	s_waitcnt lgkmcnt(0)
	s_barrier
	s_setprio 1
	s_waitcnt lgkmcnt(0)
	v_mfma_f32_16x16x32_bf16 v[164:167], v[88:91], v[152:155], v[164:167]
	v_mfma_f32_16x16x32_bf16 v[160:163], v[104:107], v[152:155], v[160:163]
	v_mfma_f32_16x16x32_bf16 v[132:135], v[88:91], v[168:171], v[132:135]
	v_mfma_f32_16x16x32_bf16 v[128:131], v[104:107], v[168:171], v[128:131]
	v_mfma_f32_16x16x32_bf16 v[100:103], v[88:91], v[176:179], v[100:103]
	v_mfma_f32_16x16x32_bf16 v[96:99], v[104:107], v[176:179], v[96:99]
	v_mfma_f32_16x16x32_bf16 v[76:79], v[88:91], v[206:209], v[76:79]
	v_mfma_f32_16x16x32_bf16 v[72:75], v[104:107], v[206:209], v[72:75]
	v_mfma_f32_16x16x32_bf16 v[164:167], v[92:95], v[156:159], v[164:167]
	v_mfma_f32_16x16x32_bf16 v[160:163], v[108:111], v[156:159], v[160:163]
	v_mfma_f32_16x16x32_bf16 v[132:135], v[92:95], v[172:175], v[132:135]
	v_mfma_f32_16x16x32_bf16 v[128:131], v[108:111], v[172:175], v[128:131]
	v_mfma_f32_16x16x32_bf16 v[100:103], v[92:95], v[180:183], v[100:103]
	v_mfma_f32_16x16x32_bf16 v[96:99], v[108:111], v[180:183], v[96:99]
	v_mfma_f32_16x16x32_bf16 v[76:79], v[92:95], v[210:213], v[76:79]
	v_mfma_f32_16x16x32_bf16 v[72:75], v[108:111], v[210:213], v[72:75]
	s_setprio 0
	s_setprio 1
	v_mfma_f32_16x16x32_bf16 v[148:151], v[120:123], v[152:155], v[148:151]
	v_mfma_f32_16x16x32_bf16 v[144:147], v[136:139], v[152:155], v[144:147]
	v_mfma_f32_16x16x32_bf16 v[116:119], v[120:123], v[168:171], v[116:119]
	v_mfma_f32_16x16x32_bf16 v[112:115], v[136:139], v[168:171], v[112:115]
	v_mfma_f32_16x16x32_bf16 v[84:87], v[120:123], v[176:179], v[84:87]
	v_mfma_f32_16x16x32_bf16 v[80:83], v[136:139], v[176:179], v[80:83]
	v_mfma_f32_16x16x32_bf16 v[68:71], v[120:123], v[206:209], v[68:71]
	v_mfma_f32_16x16x32_bf16 v[64:67], v[136:139], v[206:209], v[64:67]
	v_mfma_f32_16x16x32_bf16 v[148:151], v[124:127], v[156:159], v[148:151]
	v_mfma_f32_16x16x32_bf16 v[144:147], v[140:143], v[156:159], v[144:147]
	v_mfma_f32_16x16x32_bf16 v[116:119], v[124:127], v[172:175], v[116:119]
	v_mfma_f32_16x16x32_bf16 v[112:115], v[140:143], v[172:175], v[112:115]
	v_mfma_f32_16x16x32_bf16 v[84:87], v[124:127], v[180:183], v[84:87]
	v_mfma_f32_16x16x32_bf16 v[80:83], v[140:143], v[180:183], v[80:83]
	v_mfma_f32_16x16x32_bf16 v[68:71], v[124:127], v[210:213], v[68:71]
	v_mfma_f32_16x16x32_bf16 v[64:67], v[140:143], v[210:213], v[64:67]
	s_setprio 0
	s_barrier
	s_add_i32 s49, s39, s28
	v_lshl_add_u64 v[214:215], s[20:21], 0, v[192:193]
	s_mov_b32 m0, s49
	ds_read_b128 v[152:155], v228 offset:16384
	ds_read_b128 v[156:159], v228 offset:17408
	ds_read_b128 v[168:171], v228 offset:18432
	ds_read_b128 v[172:175], v228 offset:19456
	ds_read_b128 v[176:179], v228 offset:20480
	ds_read_b128 v[180:183], v228 offset:21504
	ds_read_b128 v[206:209], v228 offset:22528
	ds_read_b128 v[210:213], v228 offset:23552
	global_load_lds_dwordx4 v[214:215], off
	s_add_i32 m0, s49, 0x2000
	s_add_u32 s50, s20, 0xc0000
	v_lshl_add_u64 v[216:217], s[20:21], 0, v[196:197]
	s_addc_u32 s51, s21, 0
	s_add_i32 s49, s40, s28
	global_load_lds_dwordx4 v[216:217], off
	v_lshl_add_u64 v[218:219], s[50:51], 0, v[192:193]
	s_mov_b32 m0, s49
	v_lshl_add_u64 v[220:221], s[22:23], 0, v[194:195]
	global_load_lds_dwordx4 v[218:219], off
	v_lshl_add_u64 v[218:219], s[50:51], 0, v[196:197]
	s_add_i32 m0, s49, 0x2000
	s_nop 0
	global_load_lds_dwordx4 v[218:219], off
	v_lshl_add_u64 v[218:219], s[22:23], 0, v[190:191]
	s_mov_b32 m0, s29
	s_nop 0
	global_load_lds_dwordx4 v[218:219], off
	s_mov_b32 m0, s30
	s_nop 0
	global_load_lds_dwordx4 v[220:221], off
	s_waitcnt vmcnt(8)
	s_waitcnt lgkmcnt(0)
	s_barrier
; #define PG8_STAGE(bufoff, gbase, voff) do { _Pragma("unroll") for (int _i = 0; _i < 2; ++_i) \
;         __builtin_amdgcn_global_load_lds((const unsigned*)((const char*)(gbase) + (voff)[_i]), (LAS unsigned*)(lds + (bufoff) + ldsw + _i * 8192), 16, 0, 0); } while (0)
; #define PG8_LDA(dst, b, h) do { _Pragma("unroll") for (int m = 0; m < 4; ++m) _Pragma("unroll") for (int k = 0; k < 2; ++k) dst[m][k] = *(const LAS bf16x8*)(lds + PG8_SA(b, h) + aoff + m * 2048 + k * 1024); } while (0)
; #define PG8_LDB(dst, b, h) do { _Pragma("unroll") for (int n = 0; n < 2; ++n) _Pragma("unroll") for (int k = 0; k < 2; ++k) dst[n][k] = *(const LAS bf16x8*)(lds + PG8_SB(b, h) + boff + n * 2048 + k * 1024); } while (0)
; #define PG8_MMA(ai, bj, At, Bt) do { __builtin_amdgcn_s_setprio(1); _Pragma("unroll") for (int m = 0; m < 4; ++m) _Pragma("unroll") for (int n = 0; n < 2; ++n) _Pragma("unroll") for (int k = 0; k < 2; ++k) \
;         acc[ai][bj][m][n] = __builtin_amdgcn_mfma_f32_16x16x32_bf16(Bt[n][k], At[m][k], acc[ai][bj][m][n], 0, 0, 0); __builtin_amdgcn_s_setprio(0); } while (0)
; #define PG8_WAIT_V(n) asm volatile("s_waitcnt vmcnt(" #n ")" ::: "memory")
; #define PG8_WAIT_L(n) asm volatile("s_waitcnt lgkmcnt(" #n ")" ::: "memory")
; #define PG8_BAR __builtin_amdgcn_s_barrier()
; #define PG8_SCHED __builtin_amdgcn_sched_barrier(0)
; template <class Epi, class Sched>
; __device__ __forceinline__ void gemm_phase(LAS unsigned char* lds, const Gemm g, const Sched& S, const Epi& E) {
;     ...
;             PG8_WAIT_V(8); PG8_WAIT_L(0); PG8_BAR; PG8_MMA(1, 0, At, B0); PG8_MMA(1, 1, At, B1); PG8_BAR; PG8_SCHED;
;             PG8_LDB(B0, 1, 0); PG8_LDB(B1, 1, 1); PG8_SCHED; PG8_LDA(At, 1, 0); PG8_STAGE(PG8_SA(0, 1), a2 + hstepA, voffA);
;             PG8_WAIT_V(8); PG8_WAIT_L(0); PG8_BAR; PG8_MMA(0, 0, At, B0); PG8_MMA(0, 1, At, B1); PG8_BAR; PG8_SCHED;
	s_setprio 1
	s_waitcnt lgkmcnt(0)
	v_mfma_f32_16x16x32_bf16 v[60:63], v[88:91], v[152:155], v[60:63]
	v_mfma_f32_16x16x32_bf16 v[56:59], v[104:107], v[152:155], v[56:59]
	v_mfma_f32_16x16x32_bf16 v[44:47], v[88:91], v[168:171], v[44:47]
	v_mfma_f32_16x16x32_bf16 v[40:43], v[104:107], v[168:171], v[40:43]
	v_mfma_f32_16x16x32_bf16 v[28:31], v[88:91], v[176:179], v[28:31]
	v_mfma_f32_16x16x32_bf16 v[24:27], v[104:107], v[176:179], v[24:27]
	v_mfma_f32_16x16x32_bf16 v[12:15], v[88:91], v[206:209], v[12:15]
	v_mfma_f32_16x16x32_bf16 v[8:11], v[104:107], v[206:209], v[8:11]
	v_mfma_f32_16x16x32_bf16 v[60:63], v[92:95], v[156:159], v[60:63]
	v_mfma_f32_16x16x32_bf16 v[56:59], v[108:111], v[156:159], v[56:59]
	v_mfma_f32_16x16x32_bf16 v[44:47], v[92:95], v[172:175], v[44:47]
	v_mfma_f32_16x16x32_bf16 v[40:43], v[108:111], v[172:175], v[40:43]
	v_mfma_f32_16x16x32_bf16 v[28:31], v[92:95], v[180:183], v[28:31]
	v_mfma_f32_16x16x32_bf16 v[24:27], v[108:111], v[180:183], v[24:27]
	v_mfma_f32_16x16x32_bf16 v[12:15], v[92:95], v[210:213], v[12:15]
	v_mfma_f32_16x16x32_bf16 v[8:11], v[108:111], v[210:213], v[8:11]
	s_setprio 0
	s_setprio 1
	v_mfma_f32_16x16x32_bf16 v[52:55], v[120:123], v[152:155], v[52:55]
	v_mfma_f32_16x16x32_bf16 v[48:51], v[136:139], v[152:155], v[48:51]
	v_mfma_f32_16x16x32_bf16 v[36:39], v[120:123], v[168:171], v[36:39]
	v_mfma_f32_16x16x32_bf16 v[32:35], v[136:139], v[168:171], v[32:35]
	v_mfma_f32_16x16x32_bf16 v[20:23], v[120:123], v[176:179], v[20:23]
	v_mfma_f32_16x16x32_bf16 v[16:19], v[136:139], v[176:179], v[16:19]
	v_mfma_f32_16x16x32_bf16 v[4:7], v[120:123], v[206:209], v[4:7]
	v_mfma_f32_16x16x32_bf16 v[0:3], v[136:139], v[206:209], v[0:3]
	v_mfma_f32_16x16x32_bf16 v[52:55], v[124:127], v[156:159], v[52:55]
	v_mfma_f32_16x16x32_bf16 v[48:51], v[140:143], v[156:159], v[48:51]
	v_mfma_f32_16x16x32_bf16 v[36:39], v[124:127], v[172:175], v[36:39]
	v_mfma_f32_16x16x32_bf16 v[32:35], v[140:143], v[172:175], v[32:35]
	v_mfma_f32_16x16x32_bf16 v[20:23], v[124:127], v[180:183], v[20:23]
	v_mfma_f32_16x16x32_bf16 v[16:19], v[140:143], v[180:183], v[16:19]
	v_mfma_f32_16x16x32_bf16 v[4:7], v[124:127], v[210:213], v[4:7]
	v_mfma_f32_16x16x32_bf16 v[0:3], v[140:143], v[210:213], v[0:3]
	s_setprio 0
	s_barrier
	s_add_i32 s49, 0, 0x18000
	s_add_i32 s50, 0, 0x1c000
	v_add_u32_e32 v108, s49, v224
	v_add_u32_e32 v140, s50, v224
	ds_read_b128 v[88:91], v108
	ds_read_b128 v[92:95], v108 offset:1024
	ds_read_b128 v[104:107], v108 offset:2048
	ds_read_b128 v[108:111], v108 offset:3072
	ds_read_b128 v[120:123], v140
	ds_read_b128 v[124:127], v140 offset:1024
	ds_read_b128 v[136:139], v140 offset:2048
	ds_read_b128 v[140:143], v140 offset:3072
	s_add_u32 s22, s22, 0xc0000
	s_addc_u32 s23, s23, 0
	s_mov_b32 m0, s31
	v_lshl_add_u64 v[230:231], s[22:23], 0, v[190:191]
	ds_read_b128 v[152:155], v228 offset:32768
	ds_read_b128 v[156:159], v228 offset:33792
	ds_read_b128 v[168:171], v228 offset:34816
	ds_read_b128 v[172:175], v228 offset:35840
	ds_read_b128 v[176:179], v228 offset:36864
	ds_read_b128 v[180:183], v228 offset:37888
	ds_read_b128 v[206:209], v228 offset:38912
	ds_read_b128 v[210:213], v228 offset:39936
	global_load_lds_dwordx4 v[230:231], off
	v_lshl_add_u64 v[230:231], s[22:23], 0, v[194:195]
	s_mov_b32 m0, s33
	s_nop 0
	global_load_lds_dwordx4 v[230:231], off
	s_waitcnt vmcnt(8)
	s_waitcnt lgkmcnt(0)
	s_barrier
	s_setprio 1
	s_waitcnt lgkmcnt(0)
	v_mfma_f32_16x16x32_bf16 v[164:167], v[88:91], v[152:155], v[164:167]
	v_mfma_f32_16x16x32_bf16 v[160:163], v[104:107], v[152:155], v[160:163]
	v_mfma_f32_16x16x32_bf16 v[132:135], v[88:91], v[168:171], v[132:135]
	v_mfma_f32_16x16x32_bf16 v[128:131], v[104:107], v[168:171], v[128:131]
	v_mfma_f32_16x16x32_bf16 v[100:103], v[88:91], v[176:179], v[100:103]
	v_mfma_f32_16x16x32_bf16 v[96:99], v[104:107], v[176:179], v[96:99]
	v_mfma_f32_16x16x32_bf16 v[76:79], v[88:91], v[206:209], v[76:79]
	v_mfma_f32_16x16x32_bf16 v[72:75], v[104:107], v[206:209], v[72:75]
	v_mfma_f32_16x16x32_bf16 v[164:167], v[92:95], v[156:159], v[164:167]
	v_mfma_f32_16x16x32_bf16 v[160:163], v[108:111], v[156:159], v[160:163]
	v_mfma_f32_16x16x32_bf16 v[132:135], v[92:95], v[172:175], v[132:135]
	v_mfma_f32_16x16x32_bf16 v[128:131], v[108:111], v[172:175], v[128:131]
	v_mfma_f32_16x16x32_bf16 v[100:103], v[92:95], v[180:183], v[100:103]
	v_mfma_f32_16x16x32_bf16 v[96:99], v[108:111], v[180:183], v[96:99]
	v_mfma_f32_16x16x32_bf16 v[76:79], v[92:95], v[210:213], v[76:79]
	v_mfma_f32_16x16x32_bf16 v[72:75], v[108:111], v[210:213], v[72:75]
	s_setprio 0
	s_setprio 1
	v_mfma_f32_16x16x32_bf16 v[148:151], v[120:123], v[152:155], v[148:151]
	v_mfma_f32_16x16x32_bf16 v[144:147], v[136:139], v[152:155], v[144:147]
	v_mfma_f32_16x16x32_bf16 v[116:119], v[120:123], v[168:171], v[116:119]
	v_mfma_f32_16x16x32_bf16 v[112:115], v[136:139], v[168:171], v[112:115]
	v_mfma_f32_16x16x32_bf16 v[84:87], v[120:123], v[176:179], v[84:87]
	v_mfma_f32_16x16x32_bf16 v[80:83], v[136:139], v[176:179], v[80:83]
	v_mfma_f32_16x16x32_bf16 v[68:71], v[120:123], v[206:209], v[68:71]
	v_mfma_f32_16x16x32_bf16 v[64:67], v[136:139], v[206:209], v[64:67]
	v_mfma_f32_16x16x32_bf16 v[148:151], v[124:127], v[156:159], v[148:151]
	v_mfma_f32_16x16x32_bf16 v[144:147], v[140:143], v[156:159], v[144:147]
	v_mfma_f32_16x16x32_bf16 v[116:119], v[124:127], v[172:175], v[116:119]
	v_mfma_f32_16x16x32_bf16 v[112:115], v[140:143], v[172:175], v[112:115]
	v_mfma_f32_16x16x32_bf16 v[84:87], v[124:127], v[180:183], v[84:87]
	v_mfma_f32_16x16x32_bf16 v[80:83], v[140:143], v[180:183], v[80:83]
	v_mfma_f32_16x16x32_bf16 v[68:71], v[124:127], v[210:213], v[68:71]
	v_mfma_f32_16x16x32_bf16 v[64:67], v[140:143], v[210:213], v[64:67]
	s_setprio 0
	s_barrier
; #define PG8_STAGE(bufoff, gbase, voff) do { _Pragma("unroll") for (int _i = 0; _i < 2; ++_i) \
;         __builtin_amdgcn_global_load_lds((const unsigned*)((const char*)(gbase) + (voff)[_i]), (LAS unsigned*)(lds + (bufoff) + ldsw + _i * 8192), 16, 0, 0); } while (0)
; #define PG8_LDA(dst, b, h) do { _Pragma("unroll") for (int m = 0; m < 4; ++m) _Pragma("unroll") for (int k = 0; k < 2; ++k) dst[m][k] = *(const LAS bf16x8*)(lds + PG8_SA(b, h) + aoff + m * 2048 + k * 1024); } while (0)
; #define PG8_MMA(ai, bj, At, Bt) do { __builtin_amdgcn_s_setprio(1); _Pragma("unroll") for (int m = 0; m < 4; ++m) _Pragma("unroll") for (int n = 0; n < 2; ++n) _Pragma("unroll") for (int k = 0; k < 2; ++k) \
;         acc[ai][bj][m][n] = __builtin_amdgcn_mfma_f32_16x16x32_bf16(Bt[n][k], At[m][k], acc[ai][bj][m][n], 0, 0, 0); __builtin_amdgcn_s_setprio(0); } while (0)
; #define PG8_WAIT_V(n) asm volatile("s_waitcnt vmcnt(" #n ")" ::: "memory")
; #define PG8_WAIT_L(n) asm volatile("s_waitcnt lgkmcnt(" #n ")" ::: "memory")
; #define PG8_BAR __builtin_amdgcn_s_barrier()
; #define PG8_SCHED __builtin_amdgcn_sched_barrier(0)
; template <class Epi, class Sched>
; __device__ __forceinline__ void gemm_phase(LAS unsigned char* lds, const Gemm g, const Sched& S, const Epi& E) {
;     ...
;             PG8_LDA(At, 1, 1); PG8_STAGE(PG8_SB(1, 0), b3, voffB); PG8_STAGE(PG8_SB(1, 1), b3 + hstepB, voffB); PG8_STAGE(PG8_SA(1, 0), a3, voffA);
;             PG8_WAIT_V(8); PG8_WAIT_L(0); PG8_BAR; PG8_MMA(1, 0, At, B0); PG8_MMA(1, 1, At, B1); PG8_BAR; PG8_SCHED;
;         }
	s_add_i32 s22, s49, s28
	v_lshl_add_u64 v[214:215], v[214:215], 0, s[12:13]
	s_mov_b32 m0, s22
	ds_read_b128 v[152:155], v228 offset:49152
	ds_read_b128 v[156:159], v228 offset:50176
	ds_read_b128 v[168:171], v228 offset:51200
	ds_read_b128 v[172:175], v228 offset:52224
	ds_read_b128 v[176:179], v228 offset:53248
	ds_read_b128 v[180:183], v228 offset:54272
	ds_read_b128 v[206:209], v228 offset:55296
	ds_read_b128 v[210:213], v228 offset:56320
	global_load_lds_dwordx4 v[214:215], off
	s_add_i32 m0, s22, 0x2000
	s_add_u32 s20, s20, 0xc0080
	v_lshl_add_u64 v[214:215], v[216:217], 0, s[12:13]
	s_addc_u32 s21, s21, 0
	s_add_i32 s22, s50, s28
	global_load_lds_dwordx4 v[214:215], off
	v_lshl_add_u64 v[214:215], s[20:21], 0, v[192:193]
	s_mov_b32 m0, s22
	s_nop 0
	global_load_lds_dwordx4 v[214:215], off
	v_lshl_add_u64 v[214:215], s[20:21], 0, v[196:197]
	s_add_i32 m0, s22, 0x2000
	s_nop 0
	global_load_lds_dwordx4 v[214:215], off
	v_lshl_add_u64 v[214:215], v[218:219], 0, s[12:13]
	s_mov_b32 m0, s35
	s_nop 0
	global_load_lds_dwordx4 v[214:215], off
	v_lshl_add_u64 v[214:215], v[220:221], 0, s[12:13]
	s_mov_b32 m0, s36
	s_nop 0
	global_load_lds_dwordx4 v[214:215], off
	s_waitcnt vmcnt(8)
	s_waitcnt lgkmcnt(0)
	s_barrier
	s_setprio 1
	s_waitcnt lgkmcnt(0)
	v_mfma_f32_16x16x32_bf16 v[60:63], v[88:91], v[152:155], v[60:63]
	v_mfma_f32_16x16x32_bf16 v[56:59], v[104:107], v[152:155], v[56:59]
	v_mfma_f32_16x16x32_bf16 v[44:47], v[88:91], v[168:171], v[44:47]
	v_mfma_f32_16x16x32_bf16 v[40:43], v[104:107], v[168:171], v[40:43]
	v_mfma_f32_16x16x32_bf16 v[28:31], v[88:91], v[176:179], v[28:31]
	v_mfma_f32_16x16x32_bf16 v[24:27], v[104:107], v[176:179], v[24:27]
	v_mfma_f32_16x16x32_bf16 v[12:15], v[88:91], v[206:209], v[12:15]
	v_mfma_f32_16x16x32_bf16 v[8:11], v[104:107], v[206:209], v[8:11]
	v_mfma_f32_16x16x32_bf16 v[60:63], v[92:95], v[156:159], v[60:63]
	v_mfma_f32_16x16x32_bf16 v[56:59], v[108:111], v[156:159], v[56:59]
	v_mfma_f32_16x16x32_bf16 v[44:47], v[92:95], v[172:175], v[44:47]
	v_mfma_f32_16x16x32_bf16 v[40:43], v[108:111], v[172:175], v[40:43]
	v_mfma_f32_16x16x32_bf16 v[28:31], v[92:95], v[180:183], v[28:31]
	v_mfma_f32_16x16x32_bf16 v[24:27], v[108:111], v[180:183], v[24:27]
	v_mfma_f32_16x16x32_bf16 v[12:15], v[92:95], v[210:213], v[12:15]
	v_mfma_f32_16x16x32_bf16 v[8:11], v[108:111], v[210:213], v[8:11]
	s_setprio 0
	s_setprio 1
	v_mfma_f32_16x16x32_bf16 v[52:55], v[120:123], v[152:155], v[52:55]
	v_mfma_f32_16x16x32_bf16 v[48:51], v[136:139], v[152:155], v[48:51]
	v_mfma_f32_16x16x32_bf16 v[36:39], v[120:123], v[168:171], v[36:39]
	v_mfma_f32_16x16x32_bf16 v[32:35], v[136:139], v[168:171], v[32:35]
	v_mfma_f32_16x16x32_bf16 v[20:23], v[120:123], v[176:179], v[20:23]
	v_mfma_f32_16x16x32_bf16 v[16:19], v[136:139], v[176:179], v[16:19]
	v_mfma_f32_16x16x32_bf16 v[4:7], v[120:123], v[206:209], v[4:7]
	v_mfma_f32_16x16x32_bf16 v[0:3], v[136:139], v[206:209], v[0:3]
	v_mfma_f32_16x16x32_bf16 v[52:55], v[124:127], v[156:159], v[52:55]
	v_mfma_f32_16x16x32_bf16 v[48:51], v[140:143], v[156:159], v[48:51]
	v_mfma_f32_16x16x32_bf16 v[36:39], v[124:127], v[172:175], v[36:39]
	v_mfma_f32_16x16x32_bf16 v[32:35], v[140:143], v[172:175], v[32:35]
	v_mfma_f32_16x16x32_bf16 v[20:23], v[124:127], v[180:183], v[20:23]
	v_mfma_f32_16x16x32_bf16 v[16:19], v[140:143], v[180:183], v[16:19]
	v_mfma_f32_16x16x32_bf16 v[4:7], v[124:127], v[210:213], v[4:7]
	v_mfma_f32_16x16x32_bf16 v[0:3], v[140:143], v[210:213], v[0:3]
	s_setprio 0
	s_add_i32 s48, s48, 2
	s_add_u32 s18, s18, 0x100
	s_addc_u32 s19, s19, 0
	s_add_u32 s46, s46, 0x100
	s_addc_u32 s47, s47, 0
	s_cmp_gt_u32 s48, 29
	s_barrier
	s_cbranch_scc0 .LBB0_697
	s_and_b64 vcc, exec, s[14:15]
	s_cbranch_vccz .LBB0_700
	s_barrier

; #define PG8_STAGE(bufoff, gbase, voff) do { _Pragma("unroll") for (int _i = 0; _i < 2; ++_i) \
;         __builtin_amdgcn_global_load_lds((const unsigned*)((const char*)(gbase) + (voff)[_i]), (LAS unsigned*)(lds + (bufoff) + ldsw + _i * 8192), 16, 0, 0); } while (0)
; #define PG8_LDA(dst, b, h) do { _Pragma("unroll") for (int m = 0; m < 4; ++m) _Pragma("unroll") for (int k = 0; k < 2; ++k) dst[m][k] = *(const LAS bf16x8*)(lds + PG8_SA(b, h) + aoff + m * 2048 + k * 1024); } while (0)
; #define PG8_LDB(dst, b, h) do { _Pragma("unroll") for (int n = 0; n < 2; ++n) _Pragma("unroll") for (int k = 0; k < 2; ++k) dst[n][k] = *(const LAS bf16x8*)(lds + PG8_SB(b, h) + boff + n * 2048 + k * 1024); } while (0)
; #define PG8_MMA(ai, bj, At, Bt) do { __builtin_amdgcn_s_setprio(1); _Pragma("unroll") for (int m = 0; m < 4; ++m) _Pragma("unroll") for (int n = 0; n < 2; ++n) _Pragma("unroll") for (int k = 0; k < 2; ++k) \
;         acc[ai][bj][m][n] = __builtin_amdgcn_mfma_f32_16x16x32_bf16(Bt[n][k], At[m][k], acc[ai][bj][m][n], 0, 0, 0); __builtin_amdgcn_s_setprio(0); } while (0)
; #define PG8_WAIT_V(n) asm volatile("s_waitcnt vmcnt(" #n ")" ::: "memory")
; #define PG8_WAIT_L(n) asm volatile("s_waitcnt lgkmcnt(" #n ")" ::: "memory")
; #define PG8_BAR __builtin_amdgcn_s_barrier()
; #define PG8_SCHED __builtin_amdgcn_sched_barrier(0)
; template <class Epi, class Sched>
; __device__ __forceinline__ void gemm_phase(LAS unsigned char* lds, const Gemm g, const Sched& S, const Epi& E) {
;     ...
;         for (int t = 0; t < nt; t += 2) {
;             const bool last = (t == nt - 2);
;             const char* a1 = cA + (size_t)(t + 1) * kstep;
;             const char* a2 = last ? nA : cA + (size_t)(t + 2) * kstep; const char* b2 = last ? nB : cB + (size_t)(t + 2) * kstep;
;             const char* a3 = a2 + kstep; const char* b3 = b2 + kstep;
;             PG8_LDB(B0, 0, 0); PG8_LDB(B1, 0, 1); PG8_SCHED; PG8_LDA(At, 0, 0); PG8_STAGE(PG8_SA(1, 1), a1 + hstepA, voffA);
;             PG8_WAIT_V(8); PG8_WAIT_L(0); PG8_BAR; PG8_MMA(0, 0, At, B0); PG8_MMA(0, 1, At, B1); PG8_BAR; PG8_SCHED;
;             PG8_LDA(At, 0, 1); PG8_STAGE(PG8_SB(0, 0), b2, voffB); PG8_STAGE(PG8_SB(0, 1), b2 + hstepB, voffB); PG8_STAGE(PG8_SA(0, 0), a2, voffA);
.LBB0_787:
	ds_read_b128 v[128:131], v212
	ds_read_b128 v[132:135], v212 offset:1024
	ds_read_b128 v[136:139], v212 offset:2048
	ds_read_b128 v[140:143], v212 offset:3072
	ds_read_b128 v[144:147], v213
	ds_read_b128 v[148:151], v213 offset:1024
	ds_read_b128 v[152:155], v213 offset:2048
	ds_read_b128 v[156:159], v213 offset:3072
	s_add_u32 s34, s30, 0x100
	s_addc_u32 s35, s31, 0
	s_cmp_eq_u32 s60, 28
	s_cselect_b32 s39, s23, s35
	s_cselect_b32 s38, s29, s34
	s_cselect_b32 s37, s21, s59
	s_cselect_b32 s36, s57, s58
	v_lshl_add_u64 v[220:221], s[30:31], 0, v[190:191]
	s_add_i32 m0, s33, 0xc000
	ds_read_b128 v[160:163], v214
	ds_read_b128 v[164:167], v214 offset:1024
	ds_read_b128 v[168:171], v214 offset:2048
	ds_read_b128 v[172:175], v214 offset:3072
	ds_read_b128 v[198:201], v214 offset:4096
	ds_read_b128 v[202:205], v214 offset:5120
	ds_read_b128 v[206:209], v214 offset:6144
	ds_read_b128 v[216:219], v214 offset:7168
	global_load_lds_dwordx4 v[220:221], off
	v_lshl_add_u64 v[220:221], s[30:31], 0, v[192:193]
	s_add_i32 m0, s33, 0xe000
	s_nop 0
	global_load_lds_dwordx4 v[220:221], off
	s_waitcnt vmcnt(8)
	s_waitcnt lgkmcnt(0)
	s_barrier
	s_setprio 1
	s_waitcnt lgkmcnt(0)
	v_mfma_f32_16x16x32_bf16 v[124:127], v[128:131], v[160:163], v[124:127]
	v_mfma_f32_16x16x32_bf16 v[120:123], v[136:139], v[160:163], v[120:123]
	v_mfma_f32_16x16x32_bf16 v[108:111], v[128:131], v[168:171], v[108:111]
	v_mfma_f32_16x16x32_bf16 v[104:107], v[136:139], v[168:171], v[104:107]
	v_mfma_f32_16x16x32_bf16 v[92:95], v[128:131], v[198:201], v[92:95]
	v_mfma_f32_16x16x32_bf16 v[88:91], v[136:139], v[198:201], v[88:91]
	v_mfma_f32_16x16x32_bf16 v[76:79], v[128:131], v[206:209], v[76:79]
	v_mfma_f32_16x16x32_bf16 v[72:75], v[136:139], v[206:209], v[72:75]
	v_mfma_f32_16x16x32_bf16 v[124:127], v[132:135], v[164:167], v[124:127]
	v_mfma_f32_16x16x32_bf16 v[120:123], v[140:143], v[164:167], v[120:123]
	v_mfma_f32_16x16x32_bf16 v[108:111], v[132:135], v[172:175], v[108:111]
	v_mfma_f32_16x16x32_bf16 v[104:107], v[140:143], v[172:175], v[104:107]
	v_mfma_f32_16x16x32_bf16 v[92:95], v[132:135], v[202:205], v[92:95]
	v_mfma_f32_16x16x32_bf16 v[88:91], v[140:143], v[202:205], v[88:91]
	v_mfma_f32_16x16x32_bf16 v[76:79], v[132:135], v[216:219], v[76:79]
	v_mfma_f32_16x16x32_bf16 v[72:75], v[140:143], v[216:219], v[72:75]
	s_setprio 0
	s_setprio 1
	v_mfma_f32_16x16x32_bf16 v[116:119], v[144:147], v[160:163], v[116:119]
	v_mfma_f32_16x16x32_bf16 v[112:115], v[152:155], v[160:163], v[112:115]
	v_mfma_f32_16x16x32_bf16 v[100:103], v[144:147], v[168:171], v[100:103]
	v_mfma_f32_16x16x32_bf16 v[96:99], v[152:155], v[168:171], v[96:99]
	v_mfma_f32_16x16x32_bf16 v[84:87], v[144:147], v[198:201], v[84:87]
	v_mfma_f32_16x16x32_bf16 v[80:83], v[152:155], v[198:201], v[80:83]
	v_mfma_f32_16x16x32_bf16 v[68:71], v[144:147], v[206:209], v[68:71]
	v_mfma_f32_16x16x32_bf16 v[64:67], v[152:155], v[206:209], v[64:67]
	v_mfma_f32_16x16x32_bf16 v[116:119], v[148:151], v[164:167], v[116:119]
	v_mfma_f32_16x16x32_bf16 v[112:115], v[156:159], v[164:167], v[112:115]
	v_mfma_f32_16x16x32_bf16 v[100:103], v[148:151], v[172:175], v[100:103]
	v_mfma_f32_16x16x32_bf16 v[96:99], v[156:159], v[172:175], v[96:99]
	v_mfma_f32_16x16x32_bf16 v[84:87], v[148:151], v[202:205], v[84:87]
	v_mfma_f32_16x16x32_bf16 v[80:83], v[156:159], v[202:205], v[80:83]
	v_mfma_f32_16x16x32_bf16 v[68:71], v[148:151], v[216:219], v[68:71]
	v_mfma_f32_16x16x32_bf16 v[64:67], v[156:159], v[216:219], v[64:67]
	s_setprio 0
	s_barrier
	s_add_i32 s30, s50, s3
	v_lshl_add_u64 v[220:221], s[36:37], 0, v[178:179]
	s_mov_b32 m0, s30
	ds_read_b128 v[160:163], v214 offset:16384
	ds_read_b128 v[164:167], v214 offset:17408
	ds_read_b128 v[168:171], v214 offset:18432
	ds_read_b128 v[172:175], v214 offset:19456
	ds_read_b128 v[198:201], v214 offset:20480
	ds_read_b128 v[202:205], v214 offset:21504
	ds_read_b128 v[206:209], v214 offset:22528
	ds_read_b128 v[216:219], v214 offset:23552
	global_load_lds_dwordx4 v[220:221], off
	s_add_i32 m0, s30, 0x2000
	s_add_u32 s30, s36, 0x80000
	v_lshl_add_u64 v[224:225], s[36:37], 0, v[182:183]
	s_addc_u32 s31, s37, 0
	s_add_i32 s61, s51, s3
	global_load_lds_dwordx4 v[224:225], off
	v_lshl_add_u64 v[226:227], s[30:31], 0, v[178:179]
	s_mov_b32 m0, s61
	v_lshl_add_u64 v[228:229], s[38:39], 0, v[180:181]
	global_load_lds_dwordx4 v[226:227], off
	v_lshl_add_u64 v[226:227], s[30:31], 0, v[182:183]
	s_add_i32 m0, s61, 0x2000
	s_nop 0
	global_load_lds_dwordx4 v[226:227], off
	v_lshl_add_u64 v[226:227], s[38:39], 0, v[176:177]
	s_mov_b32 m0, s33
	s_nop 0
	global_load_lds_dwordx4 v[226:227], off
	s_mov_b32 m0, s40
	s_nop 0
	global_load_lds_dwordx4 v[228:229], off
	s_waitcnt vmcnt(8)
	s_waitcnt lgkmcnt(0)
	s_barrier
; #define PG8_STAGE(bufoff, gbase, voff) do { _Pragma("unroll") for (int _i = 0; _i < 2; ++_i) \
;         __builtin_amdgcn_global_load_lds((const unsigned*)((const char*)(gbase) + (voff)[_i]), (LAS unsigned*)(lds + (bufoff) + ldsw + _i * 8192), 16, 0, 0); } while (0)
; #define PG8_LDA(dst, b, h) do { _Pragma("unroll") for (int m = 0; m < 4; ++m) _Pragma("unroll") for (int k = 0; k < 2; ++k) dst[m][k] = *(const LAS bf16x8*)(lds + PG8_SA(b, h) + aoff + m * 2048 + k * 1024); } while (0)
; #define PG8_LDB(dst, b, h) do { _Pragma("unroll") for (int n = 0; n < 2; ++n) _Pragma("unroll") for (int k = 0; k < 2; ++k) dst[n][k] = *(const LAS bf16x8*)(lds + PG8_SB(b, h) + boff + n * 2048 + k * 1024); } while (0)
; #define PG8_MMA(ai, bj, At, Bt) do { __builtin_amdgcn_s_setprio(1); _Pragma("unroll") for (int m = 0; m < 4; ++m) _Pragma("unroll") for (int n = 0; n < 2; ++n) _Pragma("unroll") for (int k = 0; k < 2; ++k) \
;         acc[ai][bj][m][n] = __builtin_amdgcn_mfma_f32_16x16x32_bf16(Bt[n][k], At[m][k], acc[ai][bj][m][n], 0, 0, 0); __builtin_amdgcn_s_setprio(0); } while (0)
; #define PG8_WAIT_V(n) asm volatile("s_waitcnt vmcnt(" #n ")" ::: "memory")
; #define PG8_WAIT_L(n) asm volatile("s_waitcnt lgkmcnt(" #n ")" ::: "memory")
; #define PG8_BAR __builtin_amdgcn_s_barrier()
; #define PG8_SCHED __builtin_amdgcn_sched_barrier(0)
; template <class Epi, class Sched>
; __device__ __forceinline__ void gemm_phase(LAS unsigned char* lds, const Gemm g, const Sched& S, const Epi& E) {
;     ...
;             PG8_WAIT_V(8); PG8_WAIT_L(0); PG8_BAR; PG8_MMA(1, 0, At, B0); PG8_MMA(1, 1, At, B1); PG8_BAR; PG8_SCHED;
;             PG8_LDB(B0, 1, 0); PG8_LDB(B1, 1, 1); PG8_SCHED; PG8_LDA(At, 1, 0); PG8_STAGE(PG8_SA(0, 1), a2 + hstepA, voffA);
;             PG8_WAIT_V(8); PG8_WAIT_L(0); PG8_BAR; PG8_MMA(0, 0, At, B0); PG8_MMA(0, 1, At, B1); PG8_BAR; PG8_SCHED;
	s_setprio 1
	s_waitcnt lgkmcnt(0)
	v_mfma_f32_16x16x32_bf16 v[60:63], v[128:131], v[160:163], v[60:63]
	v_mfma_f32_16x16x32_bf16 v[56:59], v[136:139], v[160:163], v[56:59]
	v_mfma_f32_16x16x32_bf16 v[44:47], v[128:131], v[168:171], v[44:47]
	v_mfma_f32_16x16x32_bf16 v[40:43], v[136:139], v[168:171], v[40:43]
	v_mfma_f32_16x16x32_bf16 v[28:31], v[128:131], v[198:201], v[28:31]
	v_mfma_f32_16x16x32_bf16 v[24:27], v[136:139], v[198:201], v[24:27]
	v_mfma_f32_16x16x32_bf16 v[12:15], v[128:131], v[206:209], v[12:15]
	v_mfma_f32_16x16x32_bf16 v[8:11], v[136:139], v[206:209], v[8:11]
	v_mfma_f32_16x16x32_bf16 v[60:63], v[132:135], v[164:167], v[60:63]
	v_mfma_f32_16x16x32_bf16 v[56:59], v[140:143], v[164:167], v[56:59]
	v_mfma_f32_16x16x32_bf16 v[44:47], v[132:135], v[172:175], v[44:47]
	v_mfma_f32_16x16x32_bf16 v[40:43], v[140:143], v[172:175], v[40:43]
	v_mfma_f32_16x16x32_bf16 v[28:31], v[132:135], v[202:205], v[28:31]
	v_mfma_f32_16x16x32_bf16 v[24:27], v[140:143], v[202:205], v[24:27]
	v_mfma_f32_16x16x32_bf16 v[12:15], v[132:135], v[216:219], v[12:15]
	v_mfma_f32_16x16x32_bf16 v[8:11], v[140:143], v[216:219], v[8:11]
	s_setprio 0
	s_setprio 1
	v_mfma_f32_16x16x32_bf16 v[52:55], v[144:147], v[160:163], v[52:55]
	v_mfma_f32_16x16x32_bf16 v[48:51], v[152:155], v[160:163], v[48:51]
	v_mfma_f32_16x16x32_bf16 v[36:39], v[144:147], v[168:171], v[36:39]
	v_mfma_f32_16x16x32_bf16 v[32:35], v[152:155], v[168:171], v[32:35]
	v_mfma_f32_16x16x32_bf16 v[20:23], v[144:147], v[198:201], v[20:23]
	v_mfma_f32_16x16x32_bf16 v[16:19], v[152:155], v[198:201], v[16:19]
	v_mfma_f32_16x16x32_bf16 v[4:7], v[144:147], v[206:209], v[4:7]
	v_mfma_f32_16x16x32_bf16 v[0:3], v[152:155], v[206:209], v[0:3]
	v_mfma_f32_16x16x32_bf16 v[52:55], v[148:151], v[164:167], v[52:55]
	v_mfma_f32_16x16x32_bf16 v[48:51], v[156:159], v[164:167], v[48:51]
	v_mfma_f32_16x16x32_bf16 v[36:39], v[148:151], v[172:175], v[36:39]
	v_mfma_f32_16x16x32_bf16 v[32:35], v[156:159], v[172:175], v[32:35]
	v_mfma_f32_16x16x32_bf16 v[20:23], v[148:151], v[202:205], v[20:23]
	v_mfma_f32_16x16x32_bf16 v[16:19], v[156:159], v[202:205], v[16:19]
	v_mfma_f32_16x16x32_bf16 v[4:7], v[148:151], v[216:219], v[4:7]
	v_mfma_f32_16x16x32_bf16 v[0:3], v[156:159], v[216:219], v[0:3]
	s_setprio 0
	s_barrier
	s_add_i32 s61, 0, 0x18000
	s_add_i32 s62, 0, 0x1c000
	v_add_u32_e32 v140, s61, v210
	v_add_u32_e32 v156, s62, v210
	ds_read_b128 v[128:131], v140
	ds_read_b128 v[132:135], v140 offset:1024
	ds_read_b128 v[136:139], v140 offset:2048
	ds_read_b128 v[140:143], v140 offset:3072
	ds_read_b128 v[144:147], v156
	ds_read_b128 v[148:151], v156 offset:1024
	ds_read_b128 v[152:155], v156 offset:2048
	ds_read_b128 v[156:159], v156 offset:3072
	s_add_u32 s30, s38, 0x80000
	s_addc_u32 s31, s39, 0
	s_mov_b32 m0, s41
	v_lshl_add_u64 v[230:231], s[30:31], 0, v[176:177]
	ds_read_b128 v[160:163], v214 offset:32768
	ds_read_b128 v[164:167], v214 offset:33792
	ds_read_b128 v[168:171], v214 offset:34816
	ds_read_b128 v[172:175], v214 offset:35840
	ds_read_b128 v[198:201], v214 offset:36864
	ds_read_b128 v[202:205], v214 offset:37888
	ds_read_b128 v[206:209], v214 offset:38912
	ds_read_b128 v[216:219], v214 offset:39936
	global_load_lds_dwordx4 v[230:231], off
	v_lshl_add_u64 v[230:231], s[30:31], 0, v[180:181]
	s_mov_b32 m0, s42
	s_nop 0
	global_load_lds_dwordx4 v[230:231], off
	s_waitcnt vmcnt(8)
	s_waitcnt lgkmcnt(0)
	s_barrier
	s_setprio 1
	s_waitcnt lgkmcnt(0)
	v_mfma_f32_16x16x32_bf16 v[124:127], v[128:131], v[160:163], v[124:127]
	v_mfma_f32_16x16x32_bf16 v[120:123], v[136:139], v[160:163], v[120:123]
	v_mfma_f32_16x16x32_bf16 v[108:111], v[128:131], v[168:171], v[108:111]
	v_mfma_f32_16x16x32_bf16 v[104:107], v[136:139], v[168:171], v[104:107]
	v_mfma_f32_16x16x32_bf16 v[92:95], v[128:131], v[198:201], v[92:95]
	v_mfma_f32_16x16x32_bf16 v[88:91], v[136:139], v[198:201], v[88:91]
	v_mfma_f32_16x16x32_bf16 v[76:79], v[128:131], v[206:209], v[76:79]
	v_mfma_f32_16x16x32_bf16 v[72:75], v[136:139], v[206:209], v[72:75]
	v_mfma_f32_16x16x32_bf16 v[124:127], v[132:135], v[164:167], v[124:127]
	v_mfma_f32_16x16x32_bf16 v[120:123], v[140:143], v[164:167], v[120:123]
	v_mfma_f32_16x16x32_bf16 v[108:111], v[132:135], v[172:175], v[108:111]
	v_mfma_f32_16x16x32_bf16 v[104:107], v[140:143], v[172:175], v[104:107]
	v_mfma_f32_16x16x32_bf16 v[92:95], v[132:135], v[202:205], v[92:95]
	v_mfma_f32_16x16x32_bf16 v[88:91], v[140:143], v[202:205], v[88:91]
	v_mfma_f32_16x16x32_bf16 v[76:79], v[132:135], v[216:219], v[76:79]
	v_mfma_f32_16x16x32_bf16 v[72:75], v[140:143], v[216:219], v[72:75]
	s_setprio 0
	s_setprio 1
	v_mfma_f32_16x16x32_bf16 v[116:119], v[144:147], v[160:163], v[116:119]
	v_mfma_f32_16x16x32_bf16 v[112:115], v[152:155], v[160:163], v[112:115]
	v_mfma_f32_16x16x32_bf16 v[100:103], v[144:147], v[168:171], v[100:103]
	v_mfma_f32_16x16x32_bf16 v[96:99], v[152:155], v[168:171], v[96:99]
	v_mfma_f32_16x16x32_bf16 v[84:87], v[144:147], v[198:201], v[84:87]
	v_mfma_f32_16x16x32_bf16 v[80:83], v[152:155], v[198:201], v[80:83]
	v_mfma_f32_16x16x32_bf16 v[68:71], v[144:147], v[206:209], v[68:71]
	v_mfma_f32_16x16x32_bf16 v[64:67], v[152:155], v[206:209], v[64:67]
	v_mfma_f32_16x16x32_bf16 v[116:119], v[148:151], v[164:167], v[116:119]
	v_mfma_f32_16x16x32_bf16 v[112:115], v[156:159], v[164:167], v[112:115]
	v_mfma_f32_16x16x32_bf16 v[100:103], v[148:151], v[172:175], v[100:103]
	v_mfma_f32_16x16x32_bf16 v[96:99], v[156:159], v[172:175], v[96:99]
	v_mfma_f32_16x16x32_bf16 v[84:87], v[148:151], v[202:205], v[84:87]
	v_mfma_f32_16x16x32_bf16 v[80:83], v[156:159], v[202:205], v[80:83]
	v_mfma_f32_16x16x32_bf16 v[68:71], v[148:151], v[216:219], v[68:71]
	v_mfma_f32_16x16x32_bf16 v[64:67], v[156:159], v[216:219], v[64:67]
	s_setprio 0
	s_barrier
; #define PG8_STAGE(bufoff, gbase, voff) do { _Pragma("unroll") for (int _i = 0; _i < 2; ++_i) \
;         __builtin_amdgcn_global_load_lds((const unsigned*)((const char*)(gbase) + (voff)[_i]), (LAS unsigned*)(lds + (bufoff) + ldsw + _i * 8192), 16, 0, 0); } while (0)
; #define PG8_LDA(dst, b, h) do { _Pragma("unroll") for (int m = 0; m < 4; ++m) _Pragma("unroll") for (int k = 0; k < 2; ++k) dst[m][k] = *(const LAS bf16x8*)(lds + PG8_SA(b, h) + aoff + m * 2048 + k * 1024); } while (0)
; #define PG8_MMA(ai, bj, At, Bt) do { __builtin_amdgcn_s_setprio(1); _Pragma("unroll") for (int m = 0; m < 4; ++m) _Pragma("unroll") for (int n = 0; n < 2; ++n) _Pragma("unroll") for (int k = 0; k < 2; ++k) \
;         acc[ai][bj][m][n] = __builtin_amdgcn_mfma_f32_16x16x32_bf16(Bt[n][k], At[m][k], acc[ai][bj][m][n], 0, 0, 0); __builtin_amdgcn_s_setprio(0); } while (0)
; #define PG8_WAIT_V(n) asm volatile("s_waitcnt vmcnt(" #n ")" ::: "memory")
; #define PG8_WAIT_L(n) asm volatile("s_waitcnt lgkmcnt(" #n ")" ::: "memory")
; #define PG8_BAR __builtin_amdgcn_s_barrier()
; #define PG8_SCHED __builtin_amdgcn_sched_barrier(0)
; template <class Epi, class Sched>
; __device__ __forceinline__ void gemm_phase(LAS unsigned char* lds, const Gemm g, const Sched& S, const Epi& E) {
;     ...
;             PG8_LDA(At, 1, 1); PG8_STAGE(PG8_SB(1, 0), b3, voffB); PG8_STAGE(PG8_SB(1, 1), b3 + hstepB, voffB); PG8_STAGE(PG8_SA(1, 0), a3, voffA);
;             PG8_WAIT_V(8); PG8_WAIT_L(0); PG8_BAR; PG8_MMA(1, 0, At, B0); PG8_MMA(1, 1, At, B1); PG8_BAR; PG8_SCHED;
;         }
	s_add_i32 s30, s61, s3
	v_lshl_add_u64 v[220:221], v[220:221], 0, s[10:11]
	s_mov_b32 m0, s30
	ds_read_b128 v[160:163], v214 offset:49152
	ds_read_b128 v[164:167], v214 offset:50176
	ds_read_b128 v[168:171], v214 offset:51200
	ds_read_b128 v[172:175], v214 offset:52224
	ds_read_b128 v[198:201], v214 offset:53248
	ds_read_b128 v[202:205], v214 offset:54272
	ds_read_b128 v[206:209], v214 offset:55296
	ds_read_b128 v[216:219], v214 offset:56320
	global_load_lds_dwordx4 v[220:221], off
	s_add_i32 m0, s30, 0x2000
	s_add_u32 s30, s36, 0x80080
	v_lshl_add_u64 v[220:221], v[224:225], 0, s[10:11]
	s_addc_u32 s31, s37, 0
	s_add_i32 s36, s62, s3
	global_load_lds_dwordx4 v[220:221], off
	v_lshl_add_u64 v[220:221], s[30:31], 0, v[178:179]
	s_mov_b32 m0, s36
	s_nop 0
	global_load_lds_dwordx4 v[220:221], off
	v_lshl_add_u64 v[220:221], s[30:31], 0, v[182:183]
	s_add_i32 m0, s36, 0x2000
	s_nop 0
	global_load_lds_dwordx4 v[220:221], off
	v_lshl_add_u64 v[220:221], v[226:227], 0, s[10:11]
	s_mov_b32 m0, s45
	s_nop 0
	global_load_lds_dwordx4 v[220:221], off
	v_lshl_add_u64 v[220:221], v[228:229], 0, s[10:11]
	s_mov_b32 m0, s46
	s_nop 0
	global_load_lds_dwordx4 v[220:221], off
	s_waitcnt vmcnt(8)
	s_waitcnt lgkmcnt(0)
	s_barrier
	s_setprio 1
	s_waitcnt lgkmcnt(0)
	v_mfma_f32_16x16x32_bf16 v[60:63], v[128:131], v[160:163], v[60:63]
	v_mfma_f32_16x16x32_bf16 v[56:59], v[136:139], v[160:163], v[56:59]
	v_mfma_f32_16x16x32_bf16 v[44:47], v[128:131], v[168:171], v[44:47]
	v_mfma_f32_16x16x32_bf16 v[40:43], v[136:139], v[168:171], v[40:43]
	v_mfma_f32_16x16x32_bf16 v[28:31], v[128:131], v[198:201], v[28:31]
	v_mfma_f32_16x16x32_bf16 v[24:27], v[136:139], v[198:201], v[24:27]
	v_mfma_f32_16x16x32_bf16 v[12:15], v[128:131], v[206:209], v[12:15]
	v_mfma_f32_16x16x32_bf16 v[8:11], v[136:139], v[206:209], v[8:11]
	v_mfma_f32_16x16x32_bf16 v[60:63], v[132:135], v[164:167], v[60:63]
	v_mfma_f32_16x16x32_bf16 v[56:59], v[140:143], v[164:167], v[56:59]
	v_mfma_f32_16x16x32_bf16 v[44:47], v[132:135], v[172:175], v[44:47]
	v_mfma_f32_16x16x32_bf16 v[40:43], v[140:143], v[172:175], v[40:43]
	v_mfma_f32_16x16x32_bf16 v[28:31], v[132:135], v[202:205], v[28:31]
	v_mfma_f32_16x16x32_bf16 v[24:27], v[140:143], v[202:205], v[24:27]
	v_mfma_f32_16x16x32_bf16 v[12:15], v[132:135], v[216:219], v[12:15]
	v_mfma_f32_16x16x32_bf16 v[8:11], v[140:143], v[216:219], v[8:11]
	s_setprio 0
	s_setprio 1
	v_mfma_f32_16x16x32_bf16 v[52:55], v[144:147], v[160:163], v[52:55]
	v_mfma_f32_16x16x32_bf16 v[48:51], v[152:155], v[160:163], v[48:51]
	v_mfma_f32_16x16x32_bf16 v[36:39], v[144:147], v[168:171], v[36:39]
	v_mfma_f32_16x16x32_bf16 v[32:35], v[152:155], v[168:171], v[32:35]
	v_mfma_f32_16x16x32_bf16 v[20:23], v[144:147], v[198:201], v[20:23]
	v_mfma_f32_16x16x32_bf16 v[16:19], v[152:155], v[198:201], v[16:19]
	v_mfma_f32_16x16x32_bf16 v[4:7], v[144:147], v[206:209], v[4:7]
	v_mfma_f32_16x16x32_bf16 v[0:3], v[152:155], v[206:209], v[0:3]
	v_mfma_f32_16x16x32_bf16 v[52:55], v[148:151], v[164:167], v[52:55]
	v_mfma_f32_16x16x32_bf16 v[48:51], v[156:159], v[164:167], v[48:51]
	v_mfma_f32_16x16x32_bf16 v[36:39], v[148:151], v[172:175], v[36:39]
	v_mfma_f32_16x16x32_bf16 v[32:35], v[156:159], v[172:175], v[32:35]
	v_mfma_f32_16x16x32_bf16 v[20:23], v[148:151], v[202:205], v[20:23]
	v_mfma_f32_16x16x32_bf16 v[16:19], v[156:159], v[202:205], v[16:19]
	v_mfma_f32_16x16x32_bf16 v[4:7], v[148:151], v[216:219], v[4:7]
	v_mfma_f32_16x16x32_bf16 v[0:3], v[156:159], v[216:219], v[0:3]
	s_setprio 0
	s_add_i32 s60, s60, 2
	s_add_u32 s58, s58, 0x100
	s_addc_u32 s59, s59, 0
	s_cmp_gt_u32 s60, 29
	s_mov_b64 s[30:31], s[34:35]
	s_barrier
	s_cbranch_scc0 .LBB0_787
	s_and_b64 vcc, exec, s[18:19]
	s_cbranch_vccz .LBB0_790
	s_barrier

; #define PG8_STAGE(bufoff, gbase, voff) do { _Pragma("unroll") for (int _i = 0; _i < 2; ++_i) \
;         __builtin_amdgcn_global_load_lds((const unsigned*)((const char*)(gbase) + (voff)[_i]), (LAS unsigned*)(lds + (bufoff) + ldsw + _i * 8192), 16, 0, 0); } while (0)
; #define PG8_LDA(dst, b, h) do { _Pragma("unroll") for (int m = 0; m < 4; ++m) _Pragma("unroll") for (int k = 0; k < 2; ++k) dst[m][k] = *(const LAS bf16x8*)(lds + PG8_SA(b, h) + aoff + m * 2048 + k * 1024); } while (0)
; #define PG8_LDB(dst, b, h) do { _Pragma("unroll") for (int n = 0; n < 2; ++n) _Pragma("unroll") for (int k = 0; k < 2; ++k) dst[n][k] = *(const LAS bf16x8*)(lds + PG8_SB(b, h) + boff + n * 2048 + k * 1024); } while (0)
; #define PG8_MMA(ai, bj, At, Bt) do { __builtin_amdgcn_s_setprio(1); _Pragma("unroll") for (int m = 0; m < 4; ++m) _Pragma("unroll") for (int n = 0; n < 2; ++n) _Pragma("unroll") for (int k = 0; k < 2; ++k) \
;         acc[ai][bj][m][n] = __builtin_amdgcn_mfma_f32_16x16x32_bf16(Bt[n][k], At[m][k], acc[ai][bj][m][n], 0, 0, 0); __builtin_amdgcn_s_setprio(0); } while (0)
; #define PG8_WAIT_V(n) asm volatile("s_waitcnt vmcnt(" #n ")" ::: "memory")
; #define PG8_WAIT_L(n) asm volatile("s_waitcnt lgkmcnt(" #n ")" ::: "memory")
; #define PG8_BAR __builtin_amdgcn_s_barrier()
; #define PG8_SCHED __builtin_amdgcn_sched_barrier(0)
; template <class Epi, class Sched>
; __device__ __forceinline__ void gemm_phase(LAS unsigned char* lds, const Gemm g, const Sched& S, const Epi& E) {
;     ...
;         for (int t = 0; t < nt; t += 2) {
;             const bool last = (t == nt - 2);
;             const char* a1 = cA + (size_t)(t + 1) * kstep;
;             const char* a2 = last ? nA : cA + (size_t)(t + 2) * kstep; const char* b2 = last ? nB : cB + (size_t)(t + 2) * kstep;
;             const char* a3 = a2 + kstep; const char* b3 = b2 + kstep;
;             PG8_LDB(B0, 0, 0); PG8_LDB(B1, 0, 1); PG8_SCHED; PG8_LDA(At, 0, 0); PG8_STAGE(PG8_SA(1, 1), a1 + hstepA, voffA);
;             PG8_WAIT_V(8); PG8_WAIT_L(0); PG8_BAR; PG8_MMA(0, 0, At, B0); PG8_MMA(0, 1, At, B1); PG8_BAR; PG8_SCHED;
;             PG8_LDA(At, 0, 1); PG8_STAGE(PG8_SB(0, 0), b2, voffB); PG8_STAGE(PG8_SB(0, 1), b2 + hstepB, voffB); PG8_STAGE(PG8_SA(0, 0), a2, voffA);
.LBB0_933:
	ds_read_b128 v[144:147], v155
	ds_read_b128 v[148:151], v155 offset:1024
	ds_read_b128 v[158:161], v155 offset:2048
	ds_read_b128 v[162:165], v155 offset:3072
	ds_read_b128 v[166:169], v156
	ds_read_b128 v[170:173], v156 offset:1024
	ds_read_b128 v[174:177], v156 offset:2048
	ds_read_b128 v[178:181], v156 offset:3072
	s_add_u32 s36, s34, 0xfff80080
	s_addc_u32 s37, s35, -1
	s_cmp_eq_u32 s60, 28
	s_cselect_b32 s39, s27, s37
	s_cselect_b32 s38, s56, s36
	s_cselect_b32 s37, s25, s59
	s_cselect_b32 s36, s57, s58
	v_lshl_add_u64 v[182:183], s[34:35], 0, v[136:137]
	s_add_i32 m0, s41, 0xc000
	ds_read_b128 v[190:193], v157
	ds_read_b128 v[194:197], v157 offset:1024
	ds_read_b128 v[198:201], v157 offset:2048
	ds_read_b128 v[202:205], v157 offset:3072
	ds_read_b128 v[206:209], v157 offset:4096
	ds_read_b128 v[210:213], v157 offset:5120
	ds_read_b128 v[214:217], v157 offset:6144
	ds_read_b128 v[218:221], v157 offset:7168
	global_load_lds_dwordx4 v[182:183], off
	v_lshl_add_u64 v[182:183], s[34:35], 0, v[138:139]
	s_add_i32 m0, s41, 0xe000
	s_nop 0
	global_load_lds_dwordx4 v[182:183], off
	s_waitcnt vmcnt(8)
	s_waitcnt lgkmcnt(0)
	s_barrier
	s_setprio 1
	s_waitcnt lgkmcnt(0)
	v_mfma_f32_16x16x32_bf16 v[124:127], v[144:147], v[190:193], v[124:127]
	v_mfma_f32_16x16x32_bf16 v[120:123], v[158:161], v[190:193], v[120:123]
	v_mfma_f32_16x16x32_bf16 v[108:111], v[144:147], v[198:201], v[108:111]
	v_mfma_f32_16x16x32_bf16 v[104:107], v[158:161], v[198:201], v[104:107]
	v_mfma_f32_16x16x32_bf16 v[92:95], v[144:147], v[206:209], v[92:95]
	v_mfma_f32_16x16x32_bf16 v[88:91], v[158:161], v[206:209], v[88:91]
	v_mfma_f32_16x16x32_bf16 v[76:79], v[144:147], v[214:217], v[76:79]
	v_mfma_f32_16x16x32_bf16 v[72:75], v[158:161], v[214:217], v[72:75]
	v_mfma_f32_16x16x32_bf16 v[124:127], v[148:151], v[194:197], v[124:127]
	v_mfma_f32_16x16x32_bf16 v[120:123], v[162:165], v[194:197], v[120:123]
	v_mfma_f32_16x16x32_bf16 v[108:111], v[148:151], v[202:205], v[108:111]
	v_mfma_f32_16x16x32_bf16 v[104:107], v[162:165], v[202:205], v[104:107]
	v_mfma_f32_16x16x32_bf16 v[92:95], v[148:151], v[210:213], v[92:95]
	v_mfma_f32_16x16x32_bf16 v[88:91], v[162:165], v[210:213], v[88:91]
	v_mfma_f32_16x16x32_bf16 v[76:79], v[148:151], v[218:221], v[76:79]
	v_mfma_f32_16x16x32_bf16 v[72:75], v[162:165], v[218:221], v[72:75]
	s_setprio 0
	s_setprio 1
	v_mfma_f32_16x16x32_bf16 v[116:119], v[166:169], v[190:193], v[116:119]
	v_mfma_f32_16x16x32_bf16 v[112:115], v[174:177], v[190:193], v[112:115]
	v_mfma_f32_16x16x32_bf16 v[100:103], v[166:169], v[198:201], v[100:103]
	v_mfma_f32_16x16x32_bf16 v[96:99], v[174:177], v[198:201], v[96:99]
	v_mfma_f32_16x16x32_bf16 v[84:87], v[166:169], v[206:209], v[84:87]
	v_mfma_f32_16x16x32_bf16 v[80:83], v[174:177], v[206:209], v[80:83]
	v_mfma_f32_16x16x32_bf16 v[68:71], v[166:169], v[214:217], v[68:71]
	v_mfma_f32_16x16x32_bf16 v[64:67], v[174:177], v[214:217], v[64:67]
	v_mfma_f32_16x16x32_bf16 v[116:119], v[170:173], v[194:197], v[116:119]
	v_mfma_f32_16x16x32_bf16 v[112:115], v[178:181], v[194:197], v[112:115]
	v_mfma_f32_16x16x32_bf16 v[100:103], v[170:173], v[202:205], v[100:103]
	v_mfma_f32_16x16x32_bf16 v[96:99], v[178:181], v[202:205], v[96:99]
	v_mfma_f32_16x16x32_bf16 v[84:87], v[170:173], v[210:213], v[84:87]
	v_mfma_f32_16x16x32_bf16 v[80:83], v[178:181], v[210:213], v[80:83]
	v_mfma_f32_16x16x32_bf16 v[68:71], v[170:173], v[218:221], v[68:71]
	v_mfma_f32_16x16x32_bf16 v[64:67], v[178:181], v[218:221], v[64:67]
	s_setprio 0
	s_barrier
	s_add_i32 s61, s50, s3
	v_lshl_add_u64 v[182:183], s[36:37], 0, v[132:133]
	s_mov_b32 m0, s61
	ds_read_b128 v[190:193], v157 offset:16384
	ds_read_b128 v[194:197], v157 offset:17408
	ds_read_b128 v[198:201], v157 offset:18432
	ds_read_b128 v[202:205], v157 offset:19456
	ds_read_b128 v[206:209], v157 offset:20480
	ds_read_b128 v[210:213], v157 offset:21504
	ds_read_b128 v[214:217], v157 offset:22528
	ds_read_b128 v[218:221], v157 offset:23552
	global_load_lds_dwordx4 v[182:183], off
	s_add_i32 m0, s61, 0x2000
	s_add_u32 s62, s36, 0x80000
	v_lshl_add_u64 v[224:225], s[36:37], 0, v[128:129]
	s_addc_u32 s63, s37, 0
	s_add_i32 s61, s51, s3
	global_load_lds_dwordx4 v[224:225], off
	v_lshl_add_u64 v[226:227], s[62:63], 0, v[132:133]
	s_mov_b32 m0, s61
	v_lshl_add_u64 v[228:229], s[38:39], 0, v[130:131]
	global_load_lds_dwordx4 v[226:227], off
	v_lshl_add_u64 v[226:227], s[62:63], 0, v[128:129]
	s_add_i32 m0, s61, 0x2000
	s_nop 0
	global_load_lds_dwordx4 v[226:227], off
	v_lshl_add_u64 v[226:227], s[38:39], 0, v[134:135]
	s_mov_b32 m0, s41
	s_nop 0
	global_load_lds_dwordx4 v[226:227], off
	s_mov_b32 m0, s42
	s_nop 0
	global_load_lds_dwordx4 v[228:229], off
	s_waitcnt vmcnt(8)
	s_waitcnt lgkmcnt(0)
	s_barrier
; #define PG8_STAGE(bufoff, gbase, voff) do { _Pragma("unroll") for (int _i = 0; _i < 2; ++_i) \
;         __builtin_amdgcn_global_load_lds((const unsigned*)((const char*)(gbase) + (voff)[_i]), (LAS unsigned*)(lds + (bufoff) + ldsw + _i * 8192), 16, 0, 0); } while (0)
; #define PG8_LDA(dst, b, h) do { _Pragma("unroll") for (int m = 0; m < 4; ++m) _Pragma("unroll") for (int k = 0; k < 2; ++k) dst[m][k] = *(const LAS bf16x8*)(lds + PG8_SA(b, h) + aoff + m * 2048 + k * 1024); } while (0)
; #define PG8_LDB(dst, b, h) do { _Pragma("unroll") for (int n = 0; n < 2; ++n) _Pragma("unroll") for (int k = 0; k < 2; ++k) dst[n][k] = *(const LAS bf16x8*)(lds + PG8_SB(b, h) + boff + n * 2048 + k * 1024); } while (0)
; #define PG8_MMA(ai, bj, At, Bt) do { __builtin_amdgcn_s_setprio(1); _Pragma("unroll") for (int m = 0; m < 4; ++m) _Pragma("unroll") for (int n = 0; n < 2; ++n) _Pragma("unroll") for (int k = 0; k < 2; ++k) \
;         acc[ai][bj][m][n] = __builtin_amdgcn_mfma_f32_16x16x32_bf16(Bt[n][k], At[m][k], acc[ai][bj][m][n], 0, 0, 0); __builtin_amdgcn_s_setprio(0); } while (0)
; #define PG8_WAIT_V(n) asm volatile("s_waitcnt vmcnt(" #n ")" ::: "memory")
; #define PG8_WAIT_L(n) asm volatile("s_waitcnt lgkmcnt(" #n ")" ::: "memory")
; #define PG8_BAR __builtin_amdgcn_s_barrier()
; #define PG8_SCHED __builtin_amdgcn_sched_barrier(0)
; template <class Epi, class Sched>
; __device__ __forceinline__ void gemm_phase(LAS unsigned char* lds, const Gemm g, const Sched& S, const Epi& E) {
;     ...
;             PG8_WAIT_V(8); PG8_WAIT_L(0); PG8_BAR; PG8_MMA(1, 0, At, B0); PG8_MMA(1, 1, At, B1); PG8_BAR; PG8_SCHED;
;             PG8_LDB(B0, 1, 0); PG8_LDB(B1, 1, 1); PG8_SCHED; PG8_LDA(At, 1, 0); PG8_STAGE(PG8_SA(0, 1), a2 + hstepA, voffA);
;             PG8_WAIT_V(8); PG8_WAIT_L(0); PG8_BAR; PG8_MMA(0, 0, At, B0); PG8_MMA(0, 1, At, B1); PG8_BAR; PG8_SCHED;
	s_setprio 1
	s_waitcnt lgkmcnt(0)
	v_mfma_f32_16x16x32_bf16 v[60:63], v[144:147], v[190:193], v[60:63]
	v_mfma_f32_16x16x32_bf16 v[56:59], v[158:161], v[190:193], v[56:59]
	v_mfma_f32_16x16x32_bf16 v[44:47], v[144:147], v[198:201], v[44:47]
	v_mfma_f32_16x16x32_bf16 v[40:43], v[158:161], v[198:201], v[40:43]
	v_mfma_f32_16x16x32_bf16 v[28:31], v[144:147], v[206:209], v[28:31]
	v_mfma_f32_16x16x32_bf16 v[24:27], v[158:161], v[206:209], v[24:27]
	v_mfma_f32_16x16x32_bf16 v[12:15], v[144:147], v[214:217], v[12:15]
	v_mfma_f32_16x16x32_bf16 v[8:11], v[158:161], v[214:217], v[8:11]
	v_mfma_f32_16x16x32_bf16 v[60:63], v[148:151], v[194:197], v[60:63]
	v_mfma_f32_16x16x32_bf16 v[56:59], v[162:165], v[194:197], v[56:59]
	v_mfma_f32_16x16x32_bf16 v[44:47], v[148:151], v[202:205], v[44:47]
	v_mfma_f32_16x16x32_bf16 v[40:43], v[162:165], v[202:205], v[40:43]
	v_mfma_f32_16x16x32_bf16 v[28:31], v[148:151], v[210:213], v[28:31]
	v_mfma_f32_16x16x32_bf16 v[24:27], v[162:165], v[210:213], v[24:27]
	v_mfma_f32_16x16x32_bf16 v[12:15], v[148:151], v[218:221], v[12:15]
	v_mfma_f32_16x16x32_bf16 v[8:11], v[162:165], v[218:221], v[8:11]
	s_setprio 0
	s_setprio 1
	v_mfma_f32_16x16x32_bf16 v[52:55], v[166:169], v[190:193], v[52:55]
	v_mfma_f32_16x16x32_bf16 v[48:51], v[174:177], v[190:193], v[48:51]
	v_mfma_f32_16x16x32_bf16 v[36:39], v[166:169], v[198:201], v[36:39]
	v_mfma_f32_16x16x32_bf16 v[32:35], v[174:177], v[198:201], v[32:35]
	v_mfma_f32_16x16x32_bf16 v[20:23], v[166:169], v[206:209], v[20:23]
	v_mfma_f32_16x16x32_bf16 v[16:19], v[174:177], v[206:209], v[16:19]
	v_mfma_f32_16x16x32_bf16 v[4:7], v[166:169], v[214:217], v[4:7]
	v_mfma_f32_16x16x32_bf16 v[0:3], v[174:177], v[214:217], v[0:3]
	v_mfma_f32_16x16x32_bf16 v[52:55], v[170:173], v[194:197], v[52:55]
	v_mfma_f32_16x16x32_bf16 v[48:51], v[178:181], v[194:197], v[48:51]
	v_mfma_f32_16x16x32_bf16 v[36:39], v[170:173], v[202:205], v[36:39]
	v_mfma_f32_16x16x32_bf16 v[32:35], v[178:181], v[202:205], v[32:35]
	v_mfma_f32_16x16x32_bf16 v[20:23], v[170:173], v[210:213], v[20:23]
	v_mfma_f32_16x16x32_bf16 v[16:19], v[178:181], v[210:213], v[16:19]
	v_mfma_f32_16x16x32_bf16 v[4:7], v[170:173], v[218:221], v[4:7]
	v_mfma_f32_16x16x32_bf16 v[0:3], v[178:181], v[218:221], v[0:3]
	s_setprio 0
	s_barrier
	s_add_i32 s61, 0, 0x18000
	s_add_i32 s62, 0, 0x1c000
	v_add_u32_e32 v162, s61, v153
	v_add_u32_e32 v178, s62, v153
	ds_read_b128 v[144:147], v162
	ds_read_b128 v[148:151], v162 offset:1024
	ds_read_b128 v[158:161], v162 offset:2048
	ds_read_b128 v[162:165], v162 offset:3072
	ds_read_b128 v[166:169], v178
	ds_read_b128 v[170:173], v178 offset:1024
	ds_read_b128 v[174:177], v178 offset:2048
	ds_read_b128 v[178:181], v178 offset:3072
	s_add_u32 s38, s38, 0x80000
	s_addc_u32 s39, s39, 0
	s_mov_b32 m0, s43
	v_lshl_add_u64 v[230:231], s[38:39], 0, v[134:135]
	ds_read_b128 v[190:193], v157 offset:32768
	ds_read_b128 v[194:197], v157 offset:33792
	ds_read_b128 v[198:201], v157 offset:34816
	ds_read_b128 v[202:205], v157 offset:35840
	ds_read_b128 v[206:209], v157 offset:36864
	ds_read_b128 v[210:213], v157 offset:37888
	ds_read_b128 v[214:217], v157 offset:38912
	ds_read_b128 v[218:221], v157 offset:39936
	global_load_lds_dwordx4 v[230:231], off
	v_lshl_add_u64 v[230:231], s[38:39], 0, v[130:131]
	s_mov_b32 m0, s44
	s_nop 0
	global_load_lds_dwordx4 v[230:231], off
	s_waitcnt vmcnt(8)
	s_waitcnt lgkmcnt(0)
	s_barrier
	s_setprio 1
	s_waitcnt lgkmcnt(0)
	v_mfma_f32_16x16x32_bf16 v[124:127], v[144:147], v[190:193], v[124:127]
	v_mfma_f32_16x16x32_bf16 v[120:123], v[158:161], v[190:193], v[120:123]
	v_mfma_f32_16x16x32_bf16 v[108:111], v[144:147], v[198:201], v[108:111]
	v_mfma_f32_16x16x32_bf16 v[104:107], v[158:161], v[198:201], v[104:107]
	v_mfma_f32_16x16x32_bf16 v[92:95], v[144:147], v[206:209], v[92:95]
	v_mfma_f32_16x16x32_bf16 v[88:91], v[158:161], v[206:209], v[88:91]
	v_mfma_f32_16x16x32_bf16 v[76:79], v[144:147], v[214:217], v[76:79]
	v_mfma_f32_16x16x32_bf16 v[72:75], v[158:161], v[214:217], v[72:75]
	v_mfma_f32_16x16x32_bf16 v[124:127], v[148:151], v[194:197], v[124:127]
	v_mfma_f32_16x16x32_bf16 v[120:123], v[162:165], v[194:197], v[120:123]
	v_mfma_f32_16x16x32_bf16 v[108:111], v[148:151], v[202:205], v[108:111]
	v_mfma_f32_16x16x32_bf16 v[104:107], v[162:165], v[202:205], v[104:107]
	v_mfma_f32_16x16x32_bf16 v[92:95], v[148:151], v[210:213], v[92:95]
	v_mfma_f32_16x16x32_bf16 v[88:91], v[162:165], v[210:213], v[88:91]
	v_mfma_f32_16x16x32_bf16 v[76:79], v[148:151], v[218:221], v[76:79]
	v_mfma_f32_16x16x32_bf16 v[72:75], v[162:165], v[218:221], v[72:75]
	s_setprio 0
	s_setprio 1
	v_mfma_f32_16x16x32_bf16 v[116:119], v[166:169], v[190:193], v[116:119]
	v_mfma_f32_16x16x32_bf16 v[112:115], v[174:177], v[190:193], v[112:115]
	v_mfma_f32_16x16x32_bf16 v[100:103], v[166:169], v[198:201], v[100:103]
	v_mfma_f32_16x16x32_bf16 v[96:99], v[174:177], v[198:201], v[96:99]
	v_mfma_f32_16x16x32_bf16 v[84:87], v[166:169], v[206:209], v[84:87]
	v_mfma_f32_16x16x32_bf16 v[80:83], v[174:177], v[206:209], v[80:83]
	v_mfma_f32_16x16x32_bf16 v[68:71], v[166:169], v[214:217], v[68:71]
	v_mfma_f32_16x16x32_bf16 v[64:67], v[174:177], v[214:217], v[64:67]
	v_mfma_f32_16x16x32_bf16 v[116:119], v[170:173], v[194:197], v[116:119]
	v_mfma_f32_16x16x32_bf16 v[112:115], v[178:181], v[194:197], v[112:115]
	v_mfma_f32_16x16x32_bf16 v[100:103], v[170:173], v[202:205], v[100:103]
	v_mfma_f32_16x16x32_bf16 v[96:99], v[178:181], v[202:205], v[96:99]
	v_mfma_f32_16x16x32_bf16 v[84:87], v[170:173], v[210:213], v[84:87]
	v_mfma_f32_16x16x32_bf16 v[80:83], v[178:181], v[210:213], v[80:83]
	v_mfma_f32_16x16x32_bf16 v[68:71], v[170:173], v[218:221], v[68:71]
	v_mfma_f32_16x16x32_bf16 v[64:67], v[178:181], v[218:221], v[64:67]
	s_setprio 0
	s_barrier
; #define PG8_STAGE(bufoff, gbase, voff) do { _Pragma("unroll") for (int _i = 0; _i < 2; ++_i) \
;         __builtin_amdgcn_global_load_lds((const unsigned*)((const char*)(gbase) + (voff)[_i]), (LAS unsigned*)(lds + (bufoff) + ldsw + _i * 8192), 16, 0, 0); } while (0)
; #define PG8_LDA(dst, b, h) do { _Pragma("unroll") for (int m = 0; m < 4; ++m) _Pragma("unroll") for (int k = 0; k < 2; ++k) dst[m][k] = *(const LAS bf16x8*)(lds + PG8_SA(b, h) + aoff + m * 2048 + k * 1024); } while (0)
; #define PG8_MMA(ai, bj, At, Bt) do { __builtin_amdgcn_s_setprio(1); _Pragma("unroll") for (int m = 0; m < 4; ++m) _Pragma("unroll") for (int n = 0; n < 2; ++n) _Pragma("unroll") for (int k = 0; k < 2; ++k) \
;         acc[ai][bj][m][n] = __builtin_amdgcn_mfma_f32_16x16x32_bf16(Bt[n][k], At[m][k], acc[ai][bj][m][n], 0, 0, 0); __builtin_amdgcn_s_setprio(0); } while (0)
; #define PG8_WAIT_V(n) asm volatile("s_waitcnt vmcnt(" #n ")" ::: "memory")
; #define PG8_WAIT_L(n) asm volatile("s_waitcnt lgkmcnt(" #n ")" ::: "memory")
; #define PG8_BAR __builtin_amdgcn_s_barrier()
; #define PG8_SCHED __builtin_amdgcn_sched_barrier(0)
; template <class Epi, class Sched>
; __device__ __forceinline__ void gemm_phase(LAS unsigned char* lds, const Gemm g, const Sched& S, const Epi& E) {
;     ...
;             PG8_LDA(At, 1, 1); PG8_STAGE(PG8_SB(1, 0), b3, voffB); PG8_STAGE(PG8_SB(1, 1), b3 + hstepB, voffB); PG8_STAGE(PG8_SA(1, 0), a3, voffA);
;             PG8_WAIT_V(8); PG8_WAIT_L(0); PG8_BAR; PG8_MMA(1, 0, At, B0); PG8_MMA(1, 1, At, B1); PG8_BAR; PG8_SCHED;
;         }
	s_add_i32 s38, s61, s3
	v_lshl_add_u64 v[182:183], v[182:183], 0, s[10:11]
	s_mov_b32 m0, s38
	ds_read_b128 v[190:193], v157 offset:49152
	ds_read_b128 v[194:197], v157 offset:50176
	ds_read_b128 v[198:201], v157 offset:51200
	ds_read_b128 v[202:205], v157 offset:52224
	ds_read_b128 v[206:209], v157 offset:53248
	ds_read_b128 v[210:213], v157 offset:54272
	ds_read_b128 v[214:217], v157 offset:55296
	ds_read_b128 v[218:221], v157 offset:56320
	global_load_lds_dwordx4 v[182:183], off
	s_add_i32 m0, s38, 0x2000
	s_add_u32 s36, s36, 0x80080
	v_lshl_add_u64 v[182:183], v[224:225], 0, s[10:11]
	s_addc_u32 s37, s37, 0
	s_add_i32 s38, s62, s3
	global_load_lds_dwordx4 v[182:183], off
	v_lshl_add_u64 v[182:183], s[36:37], 0, v[132:133]
	s_mov_b32 m0, s38
	s_nop 0
	global_load_lds_dwordx4 v[182:183], off
	v_lshl_add_u64 v[182:183], s[36:37], 0, v[128:129]
	s_add_i32 m0, s38, 0x2000
	s_nop 0
	global_load_lds_dwordx4 v[182:183], off
	v_lshl_add_u64 v[182:183], v[226:227], 0, s[10:11]
	s_mov_b32 m0, s46
	s_nop 0
	global_load_lds_dwordx4 v[182:183], off
	v_lshl_add_u64 v[182:183], v[228:229], 0, s[10:11]
	s_mov_b32 m0, s47
	s_nop 0
	global_load_lds_dwordx4 v[182:183], off
	s_waitcnt vmcnt(8)
	s_waitcnt lgkmcnt(0)
	s_barrier
	s_setprio 1
	s_waitcnt lgkmcnt(0)
	v_mfma_f32_16x16x32_bf16 v[60:63], v[144:147], v[190:193], v[60:63]
	v_mfma_f32_16x16x32_bf16 v[56:59], v[158:161], v[190:193], v[56:59]
	v_mfma_f32_16x16x32_bf16 v[44:47], v[144:147], v[198:201], v[44:47]
	v_mfma_f32_16x16x32_bf16 v[40:43], v[158:161], v[198:201], v[40:43]
	v_mfma_f32_16x16x32_bf16 v[28:31], v[144:147], v[206:209], v[28:31]
	v_mfma_f32_16x16x32_bf16 v[24:27], v[158:161], v[206:209], v[24:27]
	v_mfma_f32_16x16x32_bf16 v[12:15], v[144:147], v[214:217], v[12:15]
	v_mfma_f32_16x16x32_bf16 v[8:11], v[158:161], v[214:217], v[8:11]
	v_mfma_f32_16x16x32_bf16 v[60:63], v[148:151], v[194:197], v[60:63]
	v_mfma_f32_16x16x32_bf16 v[56:59], v[162:165], v[194:197], v[56:59]
	v_mfma_f32_16x16x32_bf16 v[44:47], v[148:151], v[202:205], v[44:47]
	v_mfma_f32_16x16x32_bf16 v[40:43], v[162:165], v[202:205], v[40:43]
	v_mfma_f32_16x16x32_bf16 v[28:31], v[148:151], v[210:213], v[28:31]
	v_mfma_f32_16x16x32_bf16 v[24:27], v[162:165], v[210:213], v[24:27]
	v_mfma_f32_16x16x32_bf16 v[12:15], v[148:151], v[218:221], v[12:15]
	v_mfma_f32_16x16x32_bf16 v[8:11], v[162:165], v[218:221], v[8:11]
	s_setprio 0
	s_setprio 1
	v_mfma_f32_16x16x32_bf16 v[52:55], v[166:169], v[190:193], v[52:55]
	v_mfma_f32_16x16x32_bf16 v[48:51], v[174:177], v[190:193], v[48:51]
	v_mfma_f32_16x16x32_bf16 v[36:39], v[166:169], v[198:201], v[36:39]
	v_mfma_f32_16x16x32_bf16 v[32:35], v[174:177], v[198:201], v[32:35]
	v_mfma_f32_16x16x32_bf16 v[20:23], v[166:169], v[206:209], v[20:23]
	v_mfma_f32_16x16x32_bf16 v[16:19], v[174:177], v[206:209], v[16:19]
	v_mfma_f32_16x16x32_bf16 v[4:7], v[166:169], v[214:217], v[4:7]
	v_mfma_f32_16x16x32_bf16 v[0:3], v[174:177], v[214:217], v[0:3]
	v_mfma_f32_16x16x32_bf16 v[52:55], v[170:173], v[194:197], v[52:55]
	v_mfma_f32_16x16x32_bf16 v[48:51], v[178:181], v[194:197], v[48:51]
	v_mfma_f32_16x16x32_bf16 v[36:39], v[170:173], v[202:205], v[36:39]
	v_mfma_f32_16x16x32_bf16 v[32:35], v[178:181], v[202:205], v[32:35]
	v_mfma_f32_16x16x32_bf16 v[20:23], v[170:173], v[210:213], v[20:23]
	v_mfma_f32_16x16x32_bf16 v[16:19], v[178:181], v[210:213], v[16:19]
	v_mfma_f32_16x16x32_bf16 v[4:7], v[170:173], v[218:221], v[4:7]
	v_mfma_f32_16x16x32_bf16 v[0:3], v[178:181], v[218:221], v[0:3]
	s_setprio 0
	s_add_i32 s60, s60, 2
	s_add_u32 s34, s34, 0x100
	s_addc_u32 s35, s35, 0
	s_add_u32 s58, s58, 0x100
	s_addc_u32 s59, s59, 0
	s_cmp_gt_u32 s60, 29
	s_barrier
	s_cbranch_scc0 .LBB0_933
	s_and_b64 vcc, exec, s[14:15]
	s_cbranch_vccz .LBB0_936
	s_barrier

; #define PG8_STAGE(bufoff, gbase, voff) do { _Pragma("unroll") for (int _i = 0; _i < 2; ++_i) \
;         __builtin_amdgcn_global_load_lds((const unsigned*)((const char*)(gbase) + (voff)[_i]), (LAS unsigned*)(lds + (bufoff) + ldsw + _i * 8192), 16, 0, 0); } while (0)
; #define PG8_LDA(dst, b, h) do { _Pragma("unroll") for (int m = 0; m < 4; ++m) _Pragma("unroll") for (int k = 0; k < 2; ++k) dst[m][k] = *(const LAS bf16x8*)(lds + PG8_SA(b, h) + aoff + m * 2048 + k * 1024); } while (0)
; #define PG8_LDB(dst, b, h) do { _Pragma("unroll") for (int n = 0; n < 2; ++n) _Pragma("unroll") for (int k = 0; k < 2; ++k) dst[n][k] = *(const LAS bf16x8*)(lds + PG8_SB(b, h) + boff + n * 2048 + k * 1024); } while (0)
; #define PG8_MMA(ai, bj, At, Bt) do { __builtin_amdgcn_s_setprio(1); _Pragma("unroll") for (int m = 0; m < 4; ++m) _Pragma("unroll") for (int n = 0; n < 2; ++n) _Pragma("unroll") for (int k = 0; k < 2; ++k) \
;         acc[ai][bj][m][n] = __builtin_amdgcn_mfma_f32_16x16x32_bf16(Bt[n][k], At[m][k], acc[ai][bj][m][n], 0, 0, 0); __builtin_amdgcn_s_setprio(0); } while (0)
; #define PG8_WAIT_V(n) asm volatile("s_waitcnt vmcnt(" #n ")" ::: "memory")
; #define PG8_WAIT_L(n) asm volatile("s_waitcnt lgkmcnt(" #n ")" ::: "memory")
; #define PG8_BAR __builtin_amdgcn_s_barrier()
; #define PG8_SCHED __builtin_amdgcn_sched_barrier(0)
; template <class Epi, class Sched>
; __device__ __forceinline__ void gemm_phase(LAS unsigned char* lds, const Gemm g, const Sched& S, const Epi& E) {
;     ...
;         for (int t = 0; t < nt; t += 2) {
;             const bool last = (t == nt - 2);
;             const char* a1 = cA + (size_t)(t + 1) * kstep;
;             const char* a2 = last ? nA : cA + (size_t)(t + 2) * kstep; const char* b2 = last ? nB : cB + (size_t)(t + 2) * kstep;
;             const char* a3 = a2 + kstep; const char* b3 = b2 + kstep;
;             PG8_LDB(B0, 0, 0); PG8_LDB(B1, 0, 1); PG8_SCHED; PG8_LDA(At, 0, 0); PG8_STAGE(PG8_SA(1, 1), a1 + hstepA, voffA);
;             PG8_WAIT_V(8); PG8_WAIT_L(0); PG8_BAR; PG8_MMA(0, 0, At, B0); PG8_MMA(0, 1, At, B1); PG8_BAR; PG8_SCHED;
;             PG8_LDA(At, 0, 1); PG8_STAGE(PG8_SB(0, 0), b2, voffB); PG8_STAGE(PG8_SB(0, 1), b2 + hstepB, voffB); PG8_STAGE(PG8_SA(0, 0), a2, voffA);
.LBB0_1028:
	ds_read_b128 v[128:131], v191
	ds_read_b128 v[132:135], v191 offset:1024
	ds_read_b128 v[136:139], v191 offset:2048
	ds_read_b128 v[140:143], v191 offset:3072
	ds_read_b128 v[144:147], v192
	ds_read_b128 v[148:151], v192 offset:1024
	ds_read_b128 v[168:171], v192 offset:2048
	ds_read_b128 v[172:175], v192 offset:3072
	s_add_u32 s34, s30, 0x100
	s_addc_u32 s35, s31, 0
	s_cmpk_eq_i32 s55, 0x7c
	s_cselect_b32 s39, s23, s35
	s_cselect_b32 s38, s29, s34
	s_cselect_b32 s37, s21, s54
	s_cselect_b32 s36, s52, s53
	v_lshl_add_u64 v[188:189], s[30:31], 0, v[160:161]
	s_add_i32 m0, s33, 0xc000
	ds_read_b128 v[176:179], v193
	ds_read_b128 v[180:183], v193 offset:1024
	ds_read_b128 v[196:199], v193 offset:2048
	ds_read_b128 v[200:203], v193 offset:3072
	ds_read_b128 v[204:207], v193 offset:4096
	ds_read_b128 v[208:211], v193 offset:5120
	ds_read_b128 v[212:215], v193 offset:6144
	ds_read_b128 v[216:219], v193 offset:7168
	global_load_lds_dwordx4 v[188:189], off
	v_lshl_add_u64 v[188:189], s[30:31], 0, v[162:163]
	s_add_i32 m0, s33, 0xe000
	s_nop 0
	global_load_lds_dwordx4 v[188:189], off
	s_waitcnt vmcnt(8)
	s_waitcnt lgkmcnt(0)
	s_barrier
	s_setprio 1
	s_waitcnt lgkmcnt(0)
	v_mfma_f32_16x16x32_bf16 v[124:127], v[128:131], v[176:179], v[124:127]
	v_mfma_f32_16x16x32_bf16 v[120:123], v[136:139], v[176:179], v[120:123]
	v_mfma_f32_16x16x32_bf16 v[108:111], v[128:131], v[196:199], v[108:111]
	v_mfma_f32_16x16x32_bf16 v[104:107], v[136:139], v[196:199], v[104:107]
	v_mfma_f32_16x16x32_bf16 v[92:95], v[128:131], v[204:207], v[92:95]
	v_mfma_f32_16x16x32_bf16 v[88:91], v[136:139], v[204:207], v[88:91]
	v_mfma_f32_16x16x32_bf16 v[76:79], v[128:131], v[212:215], v[76:79]
	v_mfma_f32_16x16x32_bf16 v[72:75], v[136:139], v[212:215], v[72:75]
	v_mfma_f32_16x16x32_bf16 v[124:127], v[132:135], v[180:183], v[124:127]
	v_mfma_f32_16x16x32_bf16 v[120:123], v[140:143], v[180:183], v[120:123]
	v_mfma_f32_16x16x32_bf16 v[108:111], v[132:135], v[200:203], v[108:111]
	v_mfma_f32_16x16x32_bf16 v[104:107], v[140:143], v[200:203], v[104:107]
	v_mfma_f32_16x16x32_bf16 v[92:95], v[132:135], v[208:211], v[92:95]
	v_mfma_f32_16x16x32_bf16 v[88:91], v[140:143], v[208:211], v[88:91]
	v_mfma_f32_16x16x32_bf16 v[76:79], v[132:135], v[216:219], v[76:79]
	v_mfma_f32_16x16x32_bf16 v[72:75], v[140:143], v[216:219], v[72:75]
	s_setprio 0
	s_setprio 1
	v_mfma_f32_16x16x32_bf16 v[116:119], v[144:147], v[176:179], v[116:119]
	v_mfma_f32_16x16x32_bf16 v[112:115], v[168:171], v[176:179], v[112:115]
	v_mfma_f32_16x16x32_bf16 v[100:103], v[144:147], v[196:199], v[100:103]
	v_mfma_f32_16x16x32_bf16 v[96:99], v[168:171], v[196:199], v[96:99]
	v_mfma_f32_16x16x32_bf16 v[84:87], v[144:147], v[204:207], v[84:87]
	v_mfma_f32_16x16x32_bf16 v[80:83], v[168:171], v[204:207], v[80:83]
	v_mfma_f32_16x16x32_bf16 v[68:71], v[144:147], v[212:215], v[68:71]
	v_mfma_f32_16x16x32_bf16 v[64:67], v[168:171], v[212:215], v[64:67]
	v_mfma_f32_16x16x32_bf16 v[116:119], v[148:151], v[180:183], v[116:119]
	v_mfma_f32_16x16x32_bf16 v[112:115], v[172:175], v[180:183], v[112:115]
	v_mfma_f32_16x16x32_bf16 v[100:103], v[148:151], v[200:203], v[100:103]
	v_mfma_f32_16x16x32_bf16 v[96:99], v[172:175], v[200:203], v[96:99]
	v_mfma_f32_16x16x32_bf16 v[84:87], v[148:151], v[208:211], v[84:87]
	v_mfma_f32_16x16x32_bf16 v[80:83], v[172:175], v[208:211], v[80:83]
	v_mfma_f32_16x16x32_bf16 v[68:71], v[148:151], v[216:219], v[68:71]
	v_mfma_f32_16x16x32_bf16 v[64:67], v[172:175], v[216:219], v[64:67]
	s_setprio 0
	s_barrier
	s_add_i32 s30, s49, s3
	v_lshl_add_u64 v[188:189], s[36:37], 0, v[154:155]
	s_mov_b32 m0, s30
	ds_read_b128 v[176:179], v193 offset:16384
	ds_read_b128 v[180:183], v193 offset:17408
	ds_read_b128 v[196:199], v193 offset:18432
	ds_read_b128 v[200:203], v193 offset:19456
	ds_read_b128 v[204:207], v193 offset:20480
	ds_read_b128 v[208:211], v193 offset:21504
	ds_read_b128 v[212:215], v193 offset:22528
	ds_read_b128 v[216:219], v193 offset:23552
	global_load_lds_dwordx4 v[188:189], off
	s_add_i32 m0, s30, 0x2000
	s_add_u32 s30, s36, 0x200000
	v_lshl_add_u64 v[220:221], s[36:37], 0, v[158:159]
	s_addc_u32 s31, s37, 0
	s_add_i32 s56, s50, s3
	global_load_lds_dwordx4 v[220:221], off
	v_lshl_add_u64 v[222:223], s[30:31], 0, v[154:155]
	s_mov_b32 m0, s56
	v_lshl_add_u64 v[224:225], s[38:39], 0, v[156:157]
	global_load_lds_dwordx4 v[222:223], off
	v_lshl_add_u64 v[222:223], s[30:31], 0, v[158:159]
	s_add_i32 m0, s56, 0x2000
	s_nop 0
	global_load_lds_dwordx4 v[222:223], off
	v_lshl_add_u64 v[222:223], s[38:39], 0, v[152:153]
	s_mov_b32 m0, s33
	s_nop 0
	global_load_lds_dwordx4 v[222:223], off
	s_mov_b32 m0, s40
	s_nop 0
	global_load_lds_dwordx4 v[224:225], off
	s_waitcnt vmcnt(8)
	s_waitcnt lgkmcnt(0)
	s_barrier
; #define PG8_STAGE(bufoff, gbase, voff) do { _Pragma("unroll") for (int _i = 0; _i < 2; ++_i) \
;         __builtin_amdgcn_global_load_lds((const unsigned*)((const char*)(gbase) + (voff)[_i]), (LAS unsigned*)(lds + (bufoff) + ldsw + _i * 8192), 16, 0, 0); } while (0)
; #define PG8_LDA(dst, b, h) do { _Pragma("unroll") for (int m = 0; m < 4; ++m) _Pragma("unroll") for (int k = 0; k < 2; ++k) dst[m][k] = *(const LAS bf16x8*)(lds + PG8_SA(b, h) + aoff + m * 2048 + k * 1024); } while (0)
; #define PG8_LDB(dst, b, h) do { _Pragma("unroll") for (int n = 0; n < 2; ++n) _Pragma("unroll") for (int k = 0; k < 2; ++k) dst[n][k] = *(const LAS bf16x8*)(lds + PG8_SB(b, h) + boff + n * 2048 + k * 1024); } while (0)
; #define PG8_MMA(ai, bj, At, Bt) do { __builtin_amdgcn_s_setprio(1); _Pragma("unroll") for (int m = 0; m < 4; ++m) _Pragma("unroll") for (int n = 0; n < 2; ++n) _Pragma("unroll") for (int k = 0; k < 2; ++k) \
;         acc[ai][bj][m][n] = __builtin_amdgcn_mfma_f32_16x16x32_bf16(Bt[n][k], At[m][k], acc[ai][bj][m][n], 0, 0, 0); __builtin_amdgcn_s_setprio(0); } while (0)
; #define PG8_WAIT_V(n) asm volatile("s_waitcnt vmcnt(" #n ")" ::: "memory")
; #define PG8_WAIT_L(n) asm volatile("s_waitcnt lgkmcnt(" #n ")" ::: "memory")
; #define PG8_BAR __builtin_amdgcn_s_barrier()
; #define PG8_SCHED __builtin_amdgcn_sched_barrier(0)
; template <class Epi, class Sched>
; __device__ __forceinline__ void gemm_phase(LAS unsigned char* lds, const Gemm g, const Sched& S, const Epi& E) {
;     ...
;             PG8_WAIT_V(8); PG8_WAIT_L(0); PG8_BAR; PG8_MMA(1, 0, At, B0); PG8_MMA(1, 1, At, B1); PG8_BAR; PG8_SCHED;
;             PG8_LDB(B0, 1, 0); PG8_LDB(B1, 1, 1); PG8_SCHED; PG8_LDA(At, 1, 0); PG8_STAGE(PG8_SA(0, 1), a2 + hstepA, voffA);
;             PG8_WAIT_V(8); PG8_WAIT_L(0); PG8_BAR; PG8_MMA(0, 0, At, B0); PG8_MMA(0, 1, At, B1); PG8_BAR; PG8_SCHED;
	s_setprio 1
	s_waitcnt lgkmcnt(0)
	v_mfma_f32_16x16x32_bf16 v[60:63], v[128:131], v[176:179], v[60:63]
	v_mfma_f32_16x16x32_bf16 v[56:59], v[136:139], v[176:179], v[56:59]
	v_mfma_f32_16x16x32_bf16 v[44:47], v[128:131], v[196:199], v[44:47]
	v_mfma_f32_16x16x32_bf16 v[40:43], v[136:139], v[196:199], v[40:43]
	v_mfma_f32_16x16x32_bf16 v[28:31], v[128:131], v[204:207], v[28:31]
	v_mfma_f32_16x16x32_bf16 v[24:27], v[136:139], v[204:207], v[24:27]
	v_mfma_f32_16x16x32_bf16 v[12:15], v[128:131], v[212:215], v[12:15]
	v_mfma_f32_16x16x32_bf16 v[8:11], v[136:139], v[212:215], v[8:11]
	v_mfma_f32_16x16x32_bf16 v[60:63], v[132:135], v[180:183], v[60:63]
	v_mfma_f32_16x16x32_bf16 v[56:59], v[140:143], v[180:183], v[56:59]
	v_mfma_f32_16x16x32_bf16 v[44:47], v[132:135], v[200:203], v[44:47]
	v_mfma_f32_16x16x32_bf16 v[40:43], v[140:143], v[200:203], v[40:43]
	v_mfma_f32_16x16x32_bf16 v[28:31], v[132:135], v[208:211], v[28:31]
	v_mfma_f32_16x16x32_bf16 v[24:27], v[140:143], v[208:211], v[24:27]
	v_mfma_f32_16x16x32_bf16 v[12:15], v[132:135], v[216:219], v[12:15]
	v_mfma_f32_16x16x32_bf16 v[8:11], v[140:143], v[216:219], v[8:11]
	s_setprio 0
	s_setprio 1
	v_mfma_f32_16x16x32_bf16 v[52:55], v[144:147], v[176:179], v[52:55]
	v_mfma_f32_16x16x32_bf16 v[48:51], v[168:171], v[176:179], v[48:51]
	v_mfma_f32_16x16x32_bf16 v[36:39], v[144:147], v[196:199], v[36:39]
	v_mfma_f32_16x16x32_bf16 v[32:35], v[168:171], v[196:199], v[32:35]
	v_mfma_f32_16x16x32_bf16 v[20:23], v[144:147], v[204:207], v[20:23]
	v_mfma_f32_16x16x32_bf16 v[16:19], v[168:171], v[204:207], v[16:19]
	v_mfma_f32_16x16x32_bf16 v[4:7], v[144:147], v[212:215], v[4:7]
	v_mfma_f32_16x16x32_bf16 v[0:3], v[168:171], v[212:215], v[0:3]
	v_mfma_f32_16x16x32_bf16 v[52:55], v[148:151], v[180:183], v[52:55]
	v_mfma_f32_16x16x32_bf16 v[48:51], v[172:175], v[180:183], v[48:51]
	v_mfma_f32_16x16x32_bf16 v[36:39], v[148:151], v[200:203], v[36:39]
	v_mfma_f32_16x16x32_bf16 v[32:35], v[172:175], v[200:203], v[32:35]
	v_mfma_f32_16x16x32_bf16 v[20:23], v[148:151], v[208:211], v[20:23]
	v_mfma_f32_16x16x32_bf16 v[16:19], v[172:175], v[208:211], v[16:19]
	v_mfma_f32_16x16x32_bf16 v[4:7], v[148:151], v[216:219], v[4:7]
	v_mfma_f32_16x16x32_bf16 v[0:3], v[172:175], v[216:219], v[0:3]
	s_setprio 0
	s_barrier
	s_add_i32 s56, 0, 0x18000
	s_add_i32 s57, 0, 0x1c000
	v_add_u32_e32 v140, s56, v187
	v_add_u32_e32 v172, s57, v187
	ds_read_b128 v[128:131], v140
	ds_read_b128 v[132:135], v140 offset:1024
	ds_read_b128 v[136:139], v140 offset:2048
	ds_read_b128 v[140:143], v140 offset:3072
	ds_read_b128 v[144:147], v172
	ds_read_b128 v[148:151], v172 offset:1024
	ds_read_b128 v[168:171], v172 offset:2048
	ds_read_b128 v[172:175], v172 offset:3072
	s_add_u32 s30, s38, 0x200000
	s_addc_u32 s31, s39, 0
	s_mov_b32 m0, s41
	v_lshl_add_u64 v[226:227], s[30:31], 0, v[152:153]
	ds_read_b128 v[176:179], v193 offset:32768
	ds_read_b128 v[180:183], v193 offset:33792
	ds_read_b128 v[196:199], v193 offset:34816
	ds_read_b128 v[200:203], v193 offset:35840
	ds_read_b128 v[204:207], v193 offset:36864
	ds_read_b128 v[208:211], v193 offset:37888
	ds_read_b128 v[212:215], v193 offset:38912
	ds_read_b128 v[216:219], v193 offset:39936
	global_load_lds_dwordx4 v[226:227], off
	v_lshl_add_u64 v[226:227], s[30:31], 0, v[156:157]
	s_mov_b32 m0, s42
	s_nop 0
	global_load_lds_dwordx4 v[226:227], off
	s_waitcnt vmcnt(8)
	s_waitcnt lgkmcnt(0)
	s_barrier
	s_setprio 1
	s_waitcnt lgkmcnt(0)
	v_mfma_f32_16x16x32_bf16 v[124:127], v[128:131], v[176:179], v[124:127]
	v_mfma_f32_16x16x32_bf16 v[120:123], v[136:139], v[176:179], v[120:123]
	v_mfma_f32_16x16x32_bf16 v[108:111], v[128:131], v[196:199], v[108:111]
	v_mfma_f32_16x16x32_bf16 v[104:107], v[136:139], v[196:199], v[104:107]
	v_mfma_f32_16x16x32_bf16 v[92:95], v[128:131], v[204:207], v[92:95]
	v_mfma_f32_16x16x32_bf16 v[88:91], v[136:139], v[204:207], v[88:91]
	v_mfma_f32_16x16x32_bf16 v[76:79], v[128:131], v[212:215], v[76:79]
	v_mfma_f32_16x16x32_bf16 v[72:75], v[136:139], v[212:215], v[72:75]
	v_mfma_f32_16x16x32_bf16 v[124:127], v[132:135], v[180:183], v[124:127]
	v_mfma_f32_16x16x32_bf16 v[120:123], v[140:143], v[180:183], v[120:123]
	v_mfma_f32_16x16x32_bf16 v[108:111], v[132:135], v[200:203], v[108:111]
	v_mfma_f32_16x16x32_bf16 v[104:107], v[140:143], v[200:203], v[104:107]
	v_mfma_f32_16x16x32_bf16 v[92:95], v[132:135], v[208:211], v[92:95]
	v_mfma_f32_16x16x32_bf16 v[88:91], v[140:143], v[208:211], v[88:91]
	v_mfma_f32_16x16x32_bf16 v[76:79], v[132:135], v[216:219], v[76:79]
	v_mfma_f32_16x16x32_bf16 v[72:75], v[140:143], v[216:219], v[72:75]
	s_setprio 0
	s_setprio 1
	v_mfma_f32_16x16x32_bf16 v[116:119], v[144:147], v[176:179], v[116:119]
	v_mfma_f32_16x16x32_bf16 v[112:115], v[168:171], v[176:179], v[112:115]
	v_mfma_f32_16x16x32_bf16 v[100:103], v[144:147], v[196:199], v[100:103]
	v_mfma_f32_16x16x32_bf16 v[96:99], v[168:171], v[196:199], v[96:99]
	v_mfma_f32_16x16x32_bf16 v[84:87], v[144:147], v[204:207], v[84:87]
	v_mfma_f32_16x16x32_bf16 v[80:83], v[168:171], v[204:207], v[80:83]
	v_mfma_f32_16x16x32_bf16 v[68:71], v[144:147], v[212:215], v[68:71]
	v_mfma_f32_16x16x32_bf16 v[64:67], v[168:171], v[212:215], v[64:67]
	v_mfma_f32_16x16x32_bf16 v[116:119], v[148:151], v[180:183], v[116:119]
	v_mfma_f32_16x16x32_bf16 v[112:115], v[172:175], v[180:183], v[112:115]
	v_mfma_f32_16x16x32_bf16 v[100:103], v[148:151], v[200:203], v[100:103]
	v_mfma_f32_16x16x32_bf16 v[96:99], v[172:175], v[200:203], v[96:99]
	v_mfma_f32_16x16x32_bf16 v[84:87], v[148:151], v[208:211], v[84:87]
	v_mfma_f32_16x16x32_bf16 v[80:83], v[172:175], v[208:211], v[80:83]
	v_mfma_f32_16x16x32_bf16 v[68:71], v[148:151], v[216:219], v[68:71]
	v_mfma_f32_16x16x32_bf16 v[64:67], v[172:175], v[216:219], v[64:67]
	s_setprio 0
	s_barrier
; #define PG8_STAGE(bufoff, gbase, voff) do { _Pragma("unroll") for (int _i = 0; _i < 2; ++_i) \
;         __builtin_amdgcn_global_load_lds((const unsigned*)((const char*)(gbase) + (voff)[_i]), (LAS unsigned*)(lds + (bufoff) + ldsw + _i * 8192), 16, 0, 0); } while (0)
; #define PG8_LDA(dst, b, h) do { _Pragma("unroll") for (int m = 0; m < 4; ++m) _Pragma("unroll") for (int k = 0; k < 2; ++k) dst[m][k] = *(const LAS bf16x8*)(lds + PG8_SA(b, h) + aoff + m * 2048 + k * 1024); } while (0)
; #define PG8_MMA(ai, bj, At, Bt) do { __builtin_amdgcn_s_setprio(1); _Pragma("unroll") for (int m = 0; m < 4; ++m) _Pragma("unroll") for (int n = 0; n < 2; ++n) _Pragma("unroll") for (int k = 0; k < 2; ++k) \
;         acc[ai][bj][m][n] = __builtin_amdgcn_mfma_f32_16x16x32_bf16(Bt[n][k], At[m][k], acc[ai][bj][m][n], 0, 0, 0); __builtin_amdgcn_s_setprio(0); } while (0)
; #define PG8_WAIT_V(n) asm volatile("s_waitcnt vmcnt(" #n ")" ::: "memory")
; #define PG8_WAIT_L(n) asm volatile("s_waitcnt lgkmcnt(" #n ")" ::: "memory")
; #define PG8_BAR __builtin_amdgcn_s_barrier()
; #define PG8_SCHED __builtin_amdgcn_sched_barrier(0)
; template <class Epi, class Sched>
; __device__ __forceinline__ void gemm_phase(LAS unsigned char* lds, const Gemm g, const Sched& S, const Epi& E) {
;     ...
;         for (int t = 0; t < nt; t += 2) {
;             const bool last = (t == nt - 2);
;     ...
;             PG8_LDA(At, 1, 1); PG8_STAGE(PG8_SB(1, 0), b3, voffB); PG8_STAGE(PG8_SB(1, 1), b3 + hstepB, voffB); PG8_STAGE(PG8_SA(1, 0), a3, voffA);
;             PG8_WAIT_V(8); PG8_WAIT_L(0); PG8_BAR; PG8_MMA(1, 0, At, B0); PG8_MMA(1, 1, At, B1); PG8_BAR; PG8_SCHED;
	s_add_i32 s30, s56, s3
	v_lshl_add_u64 v[188:189], v[188:189], 0, s[16:17]
	s_mov_b32 m0, s30
	ds_read_b128 v[176:179], v193 offset:49152
	ds_read_b128 v[180:183], v193 offset:50176
	ds_read_b128 v[196:199], v193 offset:51200
	ds_read_b128 v[200:203], v193 offset:52224
	ds_read_b128 v[204:207], v193 offset:53248
	ds_read_b128 v[208:211], v193 offset:54272
	ds_read_b128 v[212:215], v193 offset:55296
	ds_read_b128 v[216:219], v193 offset:56320
	global_load_lds_dwordx4 v[188:189], off
	s_add_i32 m0, s30, 0x2000
	s_add_u32 s30, s36, 0x200080
	v_lshl_add_u64 v[188:189], v[220:221], 0, s[16:17]
	s_addc_u32 s31, s37, 0
	s_add_i32 s36, s57, s3
	global_load_lds_dwordx4 v[188:189], off
	v_lshl_add_u64 v[188:189], s[30:31], 0, v[154:155]
	s_mov_b32 m0, s36
	s_nop 0
	global_load_lds_dwordx4 v[188:189], off
	v_lshl_add_u64 v[188:189], s[30:31], 0, v[158:159]
	s_add_i32 m0, s36, 0x2000
	s_nop 0
	global_load_lds_dwordx4 v[188:189], off
	v_lshl_add_u64 v[188:189], v[222:223], 0, s[16:17]
	s_mov_b32 m0, s44
	s_nop 0
	global_load_lds_dwordx4 v[188:189], off
	v_lshl_add_u64 v[188:189], v[224:225], 0, s[16:17]
	s_mov_b32 m0, s45
	s_nop 0
	global_load_lds_dwordx4 v[188:189], off
	s_waitcnt vmcnt(8)
	s_waitcnt lgkmcnt(0)
	s_barrier
	s_setprio 1
	s_waitcnt lgkmcnt(0)
	v_mfma_f32_16x16x32_bf16 v[60:63], v[128:131], v[176:179], v[60:63]
	v_mfma_f32_16x16x32_bf16 v[56:59], v[136:139], v[176:179], v[56:59]
	v_mfma_f32_16x16x32_bf16 v[44:47], v[128:131], v[196:199], v[44:47]
	v_mfma_f32_16x16x32_bf16 v[40:43], v[136:139], v[196:199], v[40:43]
	v_mfma_f32_16x16x32_bf16 v[28:31], v[128:131], v[204:207], v[28:31]
	v_mfma_f32_16x16x32_bf16 v[24:27], v[136:139], v[204:207], v[24:27]
	v_mfma_f32_16x16x32_bf16 v[12:15], v[128:131], v[212:215], v[12:15]
	v_mfma_f32_16x16x32_bf16 v[8:11], v[136:139], v[212:215], v[8:11]
	v_mfma_f32_16x16x32_bf16 v[60:63], v[132:135], v[180:183], v[60:63]
	v_mfma_f32_16x16x32_bf16 v[56:59], v[140:143], v[180:183], v[56:59]
	v_mfma_f32_16x16x32_bf16 v[44:47], v[132:135], v[200:203], v[44:47]
	v_mfma_f32_16x16x32_bf16 v[40:43], v[140:143], v[200:203], v[40:43]
	v_mfma_f32_16x16x32_bf16 v[28:31], v[132:135], v[208:211], v[28:31]
	v_mfma_f32_16x16x32_bf16 v[24:27], v[140:143], v[208:211], v[24:27]
	v_mfma_f32_16x16x32_bf16 v[12:15], v[132:135], v[216:219], v[12:15]
	v_mfma_f32_16x16x32_bf16 v[8:11], v[140:143], v[216:219], v[8:11]
	s_setprio 0
	s_setprio 1
	v_mfma_f32_16x16x32_bf16 v[52:55], v[144:147], v[176:179], v[52:55]
	v_mfma_f32_16x16x32_bf16 v[48:51], v[168:171], v[176:179], v[48:51]
	v_mfma_f32_16x16x32_bf16 v[36:39], v[144:147], v[196:199], v[36:39]
	v_mfma_f32_16x16x32_bf16 v[32:35], v[168:171], v[196:199], v[32:35]
	v_mfma_f32_16x16x32_bf16 v[20:23], v[144:147], v[204:207], v[20:23]
	v_mfma_f32_16x16x32_bf16 v[16:19], v[168:171], v[204:207], v[16:19]
	v_mfma_f32_16x16x32_bf16 v[4:7], v[144:147], v[212:215], v[4:7]
	v_mfma_f32_16x16x32_bf16 v[0:3], v[168:171], v[212:215], v[0:3]
	v_mfma_f32_16x16x32_bf16 v[52:55], v[148:151], v[180:183], v[52:55]
	v_mfma_f32_16x16x32_bf16 v[48:51], v[172:175], v[180:183], v[48:51]
	v_mfma_f32_16x16x32_bf16 v[36:39], v[148:151], v[200:203], v[36:39]
	v_mfma_f32_16x16x32_bf16 v[32:35], v[172:175], v[200:203], v[32:35]
	v_mfma_f32_16x16x32_bf16 v[20:23], v[148:151], v[208:211], v[20:23]
	v_mfma_f32_16x16x32_bf16 v[16:19], v[172:175], v[208:211], v[16:19]
	v_mfma_f32_16x16x32_bf16 v[4:7], v[148:151], v[216:219], v[4:7]
	v_mfma_f32_16x16x32_bf16 v[0:3], v[172:175], v[216:219], v[0:3]
	s_setprio 0
	s_add_i32 s55, s55, 2
	s_add_u32 s53, s53, 0x100
	s_addc_u32 s54, s54, 0
	s_cmpk_gt_u32 s55, 0x7d
	s_mov_b64 s[30:31], s[34:35]
	s_barrier
	s_cbranch_scc0 .LBB0_1028
	s_and_b64 vcc, exec, s[18:19]
	s_cbranch_vccz .LBB0_1031
	s_barrier
